# v25 + attention phase: O1/O2 stores, YCAT stores and the combine's O/ZA loads marked nt (write-once/read-once traffic), K/V DMA keeps default L2 policy
# baseline (speedup 1.0000x reference)
; __device__ __forceinline__ int crow(int r,int hi){return (r&3)+8*(r>>2)+4*hi;}
; template<int THRL> __device__ __forceinline__ void attn_unit(int b,int qc,int vc,int qb,const bf16*Q,const bf16*__restrict__ K,const bf16*__restrict__ V,bf16*O,char*shm,const int tid){
;     ...
;   {auto rr=__builtin_amdgcn_permlane32_swap(__float_as_uint(l_reg),__float_as_uint(l_reg),false,false);l_reg=__uint_as_float(rr[0])+__uint_as_float(rr[1]);}
;   if(hi==0)wsf[32+r32]=l_reg;asm volatile("s_waitcnt lgkmcnt(0)":::"memory");
;   float rli[16];
;   #pragma unroll
;   for(int r=0;r<16;++r)rli[r]=__builtin_amdgcn_rcpf(wsf[32+crow(r,hi)]);
;   bf16*Ow=O+(rowbase+q0+wid*QBLK)*DM+vc;
;   { bf16*stg=(bf16*)(shm+LDS_OST)+wid*2048;
;     #pragma unroll
;     for(int r=0;r<16;++r){const int orow=crow(r,hi);
;       #pragma unroll
;       for(int d0=0;d0<2;++d0)stg[orow*64+d0*32+r32]=__float2bfloat16(o[d0][r]*rli[r]);}
;     asm volatile("s_waitcnt lgkmcnt(0)":::"memory");
;     #pragma unroll
;     for(int i=0;i<4;++i){const int row=i*8+(lane>>3),ch=lane&7; const u32x4 v=*(const u32x4*)(stg+row*64+ch*8); ATTN_STORE16(Ow+(long)row*DM+ch*8,v);} }
.Lat_epilogue:
	v_mov_b32_e32 v243, v211
	s_nop 1
	v_permlane32_swap_b32_e32 v211, v243
	v_add_f32_e32 v211, v211, v243
	ds_write_b32 v226, v211 offset:128
	s_waitcnt lgkmcnt(0)
	ds_read_b128 v[80:83], v227 offset:128
	ds_read_b128 v[84:87], v227 offset:160
	ds_read_b128 v[88:91], v227 offset:192
	ds_read_b128 v[92:95], v227 offset:224
	s_waitcnt lgkmcnt(0)
	v_rcp_f32_e32 v80, v80
	v_rcp_f32_e32 v81, v81
	v_rcp_f32_e32 v82, v82
	v_rcp_f32_e32 v83, v83
	v_rcp_f32_e32 v84, v84
	v_rcp_f32_e32 v85, v85
	v_rcp_f32_e32 v86, v86
	v_rcp_f32_e32 v87, v87
	v_rcp_f32_e32 v88, v88
	v_rcp_f32_e32 v89, v89
	v_rcp_f32_e32 v90, v90
	v_rcp_f32_e32 v91, v91
	v_rcp_f32_e32 v92, v92
	v_rcp_f32_e32 v93, v93
	v_rcp_f32_e32 v94, v94
	v_rcp_f32_e32 v95, v95
	s_nop 0
	v_mul_f32_e32 v96, v0, v80
	v_cvt_pk_bf16_f32 v96, v96, v96
	ds_write_b16 v228, v96 offset:0
	v_mul_f32_e32 v97, v1, v81
	v_cvt_pk_bf16_f32 v97, v97, v97
	ds_write_b16 v228, v97 offset:128
	v_mul_f32_e32 v98, v2, v82
	v_cvt_pk_bf16_f32 v98, v98, v98
	ds_write_b16 v228, v98 offset:256
	v_mul_f32_e32 v99, v3, v83
	v_cvt_pk_bf16_f32 v99, v99, v99
	ds_write_b16 v228, v99 offset:384
	v_mul_f32_e32 v100, v4, v84
	v_cvt_pk_bf16_f32 v100, v100, v100
	ds_write_b16 v228, v100 offset:1024
	v_mul_f32_e32 v101, v5, v85
	v_cvt_pk_bf16_f32 v101, v101, v101
	ds_write_b16 v228, v101 offset:1152
	v_mul_f32_e32 v102, v6, v86
	v_cvt_pk_bf16_f32 v102, v102, v102
	ds_write_b16 v228, v102 offset:1280
	v_mul_f32_e32 v103, v7, v87
	v_cvt_pk_bf16_f32 v103, v103, v103
	ds_write_b16 v228, v103 offset:1408
	v_mul_f32_e32 v104, v8, v88
	v_cvt_pk_bf16_f32 v104, v104, v104
	ds_write_b16 v228, v104 offset:2048
	v_mul_f32_e32 v105, v9, v89
	v_cvt_pk_bf16_f32 v105, v105, v105
	ds_write_b16 v228, v105 offset:2176
	v_mul_f32_e32 v106, v10, v90
	v_cvt_pk_bf16_f32 v106, v106, v106
	ds_write_b16 v228, v106 offset:2304
	v_mul_f32_e32 v107, v11, v91
	v_cvt_pk_bf16_f32 v107, v107, v107
	ds_write_b16 v228, v107 offset:2432
	v_mul_f32_e32 v108, v12, v92
	v_cvt_pk_bf16_f32 v108, v108, v108
	ds_write_b16 v228, v108 offset:3072
	v_mul_f32_e32 v109, v13, v93
	v_cvt_pk_bf16_f32 v109, v109, v109
	ds_write_b16 v228, v109 offset:3200
	v_mul_f32_e32 v110, v14, v94
	v_cvt_pk_bf16_f32 v110, v110, v110
	ds_write_b16 v228, v110 offset:3328
	v_mul_f32_e32 v111, v15, v95
	v_cvt_pk_bf16_f32 v111, v111, v111
	ds_write_b16 v228, v111 offset:3456
	v_mul_f32_e32 v96, v16, v80
	v_cvt_pk_bf16_f32 v96, v96, v96
	ds_write_b16 v228, v96 offset:64
	v_mul_f32_e32 v97, v17, v81
	v_cvt_pk_bf16_f32 v97, v97, v97
	ds_write_b16 v228, v97 offset:192
	v_mul_f32_e32 v98, v18, v82
	v_cvt_pk_bf16_f32 v98, v98, v98
	ds_write_b16 v228, v98 offset:320
	v_mul_f32_e32 v99, v19, v83
	v_cvt_pk_bf16_f32 v99, v99, v99
	ds_write_b16 v228, v99 offset:448
	v_mul_f32_e32 v100, v20, v84
	v_cvt_pk_bf16_f32 v100, v100, v100
	ds_write_b16 v228, v100 offset:1088
	v_mul_f32_e32 v101, v21, v85
	v_cvt_pk_bf16_f32 v101, v101, v101
	ds_write_b16 v228, v101 offset:1216
	v_mul_f32_e32 v102, v22, v86
	v_cvt_pk_bf16_f32 v102, v102, v102
	ds_write_b16 v228, v102 offset:1344
	v_mul_f32_e32 v103, v23, v87
	v_cvt_pk_bf16_f32 v103, v103, v103
	ds_write_b16 v228, v103 offset:1472
	v_mul_f32_e32 v104, v24, v88
	v_cvt_pk_bf16_f32 v104, v104, v104
	ds_write_b16 v228, v104 offset:2112
	v_mul_f32_e32 v105, v25, v89
	v_cvt_pk_bf16_f32 v105, v105, v105
	ds_write_b16 v228, v105 offset:2240
	v_mul_f32_e32 v106, v26, v90
	v_cvt_pk_bf16_f32 v106, v106, v106
	ds_write_b16 v228, v106 offset:2368
	v_mul_f32_e32 v107, v27, v91
	v_cvt_pk_bf16_f32 v107, v107, v107
	ds_write_b16 v228, v107 offset:2496
	v_mul_f32_e32 v108, v28, v92
	v_cvt_pk_bf16_f32 v108, v108, v108
	ds_write_b16 v228, v108 offset:3136
	v_mul_f32_e32 v109, v29, v93
	v_cvt_pk_bf16_f32 v109, v109, v109
	ds_write_b16 v228, v109 offset:3264
	v_mul_f32_e32 v110, v30, v94
	v_cvt_pk_bf16_f32 v110, v110, v110
	ds_write_b16 v228, v110 offset:3392
	v_mul_f32_e32 v111, v31, v95
	v_cvt_pk_bf16_f32 v111, v111, v111
	ds_write_b16 v228, v111 offset:3520
	s_waitcnt lgkmcnt(0)
	ds_read_b128 v[112:115], v229 offset:0
	ds_read_b128 v[116:119], v229 offset:1024
	ds_read_b128 v[120:123], v229 offset:2048
	ds_read_b128 v[124:127], v229 offset:3072
	s_waitcnt lgkmcnt(3)
	v_mov_b32_e32 v243, v251
	global_store_dwordx4 v243, v[112:115], s[6:7] offset:0 nt
	s_nop 1
	s_waitcnt lgkmcnt(2)
; __device__ __forceinline__ int crow(int r,int hi){return (r&3)+8*(r>>2)+4*hi;}
; template<int THRL> __device__ __forceinline__ void attn_unit(int b,int qc,int vc,int qb,const bf16*Q,const bf16*__restrict__ K,const bf16*__restrict__ V,bf16*O,char*shm,const int tid){
;     ...
;   bf16*Ow=O+(rowbase+q0+wid*QBLK)*DM+vc;
;   { bf16*stg=(bf16*)(shm+LDS_OST)+wid*2048;
;     #pragma unroll
;     for(int r=0;r<16;++r){const int orow=crow(r,hi);
;       #pragma unroll
;       for(int d0=0;d0<2;++d0)stg[orow*64+d0*32+r32]=__float2bfloat16(o[d0][r]*rli[r]);}
;     asm volatile("s_waitcnt lgkmcnt(0)":::"memory");
;     #pragma unroll
;     for(int i=0;i<4;++i){const int row=i*8+(lane>>3),ch=lane&7; const u32x4 v=*(const u32x4*)(stg+row*64+ch*8); ATTN_STORE16(Ow+(long)row*DM+ch*8,v);} }
;   asm volatile("s_waitcnt lgkmcnt(0)\n\ts_barrier":::"memory");
	v_add_u32_e32 v243, 0x4000, v243
	global_store_dwordx4 v243, v[116:119], s[6:7] offset:0 nt
	s_nop 1
	s_waitcnt lgkmcnt(1)
	v_add_u32_e32 v243, 0x4000, v243
	global_store_dwordx4 v243, v[120:123], s[6:7] offset:0 nt
	s_nop 1
	s_waitcnt lgkmcnt(0)
	v_add_u32_e32 v243, 0x4000, v243
	global_store_dwordx4 v243, v[124:127], s[6:7] offset:0 nt
	s_nop 1
	v_mul_f32_e32 v96, v32, v80
	v_cvt_pk_bf16_f32 v96, v96, v96
	ds_write_b16 v228, v96 offset:0
	v_mul_f32_e32 v97, v33, v81
	v_cvt_pk_bf16_f32 v97, v97, v97
	ds_write_b16 v228, v97 offset:128
	v_mul_f32_e32 v98, v34, v82
	v_cvt_pk_bf16_f32 v98, v98, v98
	ds_write_b16 v228, v98 offset:256
	v_mul_f32_e32 v99, v35, v83
	v_cvt_pk_bf16_f32 v99, v99, v99
	ds_write_b16 v228, v99 offset:384
	v_mul_f32_e32 v100, v36, v84
	v_cvt_pk_bf16_f32 v100, v100, v100
	ds_write_b16 v228, v100 offset:1024
	v_mul_f32_e32 v101, v37, v85
	v_cvt_pk_bf16_f32 v101, v101, v101
	ds_write_b16 v228, v101 offset:1152
	v_mul_f32_e32 v102, v38, v86
	v_cvt_pk_bf16_f32 v102, v102, v102
	ds_write_b16 v228, v102 offset:1280
	v_mul_f32_e32 v103, v39, v87
	v_cvt_pk_bf16_f32 v103, v103, v103
	ds_write_b16 v228, v103 offset:1408
	v_mul_f32_e32 v104, v40, v88
	v_cvt_pk_bf16_f32 v104, v104, v104
	ds_write_b16 v228, v104 offset:2048
	v_mul_f32_e32 v105, v41, v89
	v_cvt_pk_bf16_f32 v105, v105, v105
	ds_write_b16 v228, v105 offset:2176
	v_mul_f32_e32 v106, v42, v90
	v_cvt_pk_bf16_f32 v106, v106, v106
	ds_write_b16 v228, v106 offset:2304
	v_mul_f32_e32 v107, v43, v91
	v_cvt_pk_bf16_f32 v107, v107, v107
	ds_write_b16 v228, v107 offset:2432
	v_mul_f32_e32 v108, v44, v92
	v_cvt_pk_bf16_f32 v108, v108, v108
	ds_write_b16 v228, v108 offset:3072
	v_mul_f32_e32 v109, v45, v93
	v_cvt_pk_bf16_f32 v109, v109, v109
	ds_write_b16 v228, v109 offset:3200
	v_mul_f32_e32 v110, v46, v94
	v_cvt_pk_bf16_f32 v110, v110, v110
	ds_write_b16 v228, v110 offset:3328
	v_mul_f32_e32 v111, v47, v95
	v_cvt_pk_bf16_f32 v111, v111, v111
	ds_write_b16 v228, v111 offset:3456
	v_mul_f32_e32 v96, v48, v80
	v_cvt_pk_bf16_f32 v96, v96, v96
	ds_write_b16 v228, v96 offset:64
	v_mul_f32_e32 v97, v49, v81
	v_cvt_pk_bf16_f32 v97, v97, v97
	ds_write_b16 v228, v97 offset:192
	v_mul_f32_e32 v98, v50, v82
	v_cvt_pk_bf16_f32 v98, v98, v98
	ds_write_b16 v228, v98 offset:320
	v_mul_f32_e32 v99, v51, v83
	v_cvt_pk_bf16_f32 v99, v99, v99
	ds_write_b16 v228, v99 offset:448
	v_mul_f32_e32 v100, v52, v84
	v_cvt_pk_bf16_f32 v100, v100, v100
	ds_write_b16 v228, v100 offset:1088
	v_mul_f32_e32 v101, v53, v85
	v_cvt_pk_bf16_f32 v101, v101, v101
	ds_write_b16 v228, v101 offset:1216
	v_mul_f32_e32 v102, v54, v86
	v_cvt_pk_bf16_f32 v102, v102, v102
	ds_write_b16 v228, v102 offset:1344
	v_mul_f32_e32 v103, v55, v87
	v_cvt_pk_bf16_f32 v103, v103, v103
	ds_write_b16 v228, v103 offset:1472
	v_mul_f32_e32 v104, v56, v88
	v_cvt_pk_bf16_f32 v104, v104, v104
	ds_write_b16 v228, v104 offset:2112
	v_mul_f32_e32 v105, v57, v89
	v_cvt_pk_bf16_f32 v105, v105, v105
	ds_write_b16 v228, v105 offset:2240
	v_mul_f32_e32 v106, v58, v90
	v_cvt_pk_bf16_f32 v106, v106, v106
	ds_write_b16 v228, v106 offset:2368
	v_mul_f32_e32 v107, v59, v91
	v_cvt_pk_bf16_f32 v107, v107, v107
	ds_write_b16 v228, v107 offset:2496
	v_mul_f32_e32 v108, v60, v92
	v_cvt_pk_bf16_f32 v108, v108, v108
	ds_write_b16 v228, v108 offset:3136
	v_mul_f32_e32 v109, v61, v93
	v_cvt_pk_bf16_f32 v109, v109, v109
	ds_write_b16 v228, v109 offset:3264
	v_mul_f32_e32 v110, v62, v94
	v_cvt_pk_bf16_f32 v110, v110, v110
	ds_write_b16 v228, v110 offset:3392
	v_mul_f32_e32 v111, v63, v95
	v_cvt_pk_bf16_f32 v111, v111, v111
	ds_write_b16 v228, v111 offset:3520
	s_waitcnt lgkmcnt(0)
	ds_read_b128 v[112:115], v229 offset:0
	ds_read_b128 v[116:119], v229 offset:1024
	ds_read_b128 v[120:123], v229 offset:2048
	ds_read_b128 v[124:127], v229 offset:3072
	s_waitcnt lgkmcnt(3)
	v_mov_b32_e32 v243, v251
	global_store_dwordx4 v243, v[112:115], s[6:7] offset:128 nt
	s_nop 1
	s_waitcnt lgkmcnt(2)
	v_add_u32_e32 v243, 0x4000, v243
	global_store_dwordx4 v243, v[116:119], s[6:7] offset:128 nt
	s_nop 1
	s_waitcnt lgkmcnt(1)
	v_add_u32_e32 v243, 0x4000, v243
	global_store_dwordx4 v243, v[120:123], s[6:7] offset:128 nt
	s_nop 1
	s_waitcnt lgkmcnt(0)
	v_add_u32_e32 v243, 0x4000, v243
	global_store_dwordx4 v243, v[124:127], s[6:7] offset:128 nt
	s_nop 1
	s_waitcnt lgkmcnt(0)
	s_barrier
	s_branch .Lat_unit_done

; #define GASP __attribute__((address_space(1)))
; __global__ void __launch_bounds__(NWAVES * 64, 2) fwd_kernel(Args args) {
;     ...
;                 for (int qi = 0; qi < 4; ++qi) {
;                     const int qb = (qi == 0) ? 15 - s4 : (qi == 1) ? 8 + s4 : (qi == 2) ? 7 - s4 : s4;
;                     {
;                         asm volatile("s_waitcnt vmcnt(0)" ::: "memory");
;                         int ln = tidp & 63; asm volatile("" : "+v"(ln));
;                         unsigned char* w2 = ws; asm volatile("" : "+s"(w2));
;                         const float lambda_init = 0.8f - 0.6f * expf(-0.3f * (float)l);
;                         const float* lq1 = (const float*)ldp(L, 18); const float* lk1 = (const float*)ldp(L, 19); const float* lq2 = (const float*)ldp(L, 20); const float* lk2 = (const float*)ldp(L, 21);
;                         const float d1 = wave_sum(lq1[l * 64 + ln] * lk1[l * 64 + ln], ln), d2 = wave_sum(lq2[l * 64 + ln] * lk2[l * 64 + ln], ln);
;                         const float lam = expf(d1) - expf(d2) + lambda_init;
;                         const int c8 = (ln & 15) * 8, sub = ln >> 4;
;                         const float* sg = (const float*)ldp(L, 22) + (size_t)l * 128 + c8;
;                         const f32x4 sg0 = *(const GASP f32x4*)sg * (1.f - lambda_init), sg1 = *(const GASP f32x4*)(sg + 4) * (1.f - lambda_init);
;                         const size_t r0 = (size_t)b * SEQ + qb * 256 + wave * 32 + sub;
;                         const bf16* O1 = (const bf16*)(w2 + WS_H); const bf16* O2 = O1 + (size_t)NTOK * 1024; const bf16* ZA = (const bf16*)(w2 + WS_ZA); bf16* YCAT = (bf16*)(w2 + WS_A2);
;                         v4u pp[8], qq[8], zz[8];
; #pragma unroll
;                         for (int it = 0; it < 8; ++it) { const size_t off = (r0 + it * 4) * 1024 + h * 128 + c8;
;                             pp[it] = *(const GASP v4u*)(O1 + off); qq[it] = *(const GASP v4u*)(O2 + off);
;                             zz[it] = *(const GASP v4u*)(ZA + off); }
.Lat_unit_done:
	s_add_i32 s73, s73, 1
	s_cmp_lt_u32 s73, 4
	s_cbranch_scc1 .Lat_qi_loop
	s_add_i32 s72, s72, 1
	s_cmp_lt_u32 s72, 2
	s_cbranch_scc1 .Lat_mp_loop
	s_waitcnt vmcnt(0)
	v_and_b32_e32 v253, 15, v239
	v_lshrrev_b32_e32 v249, 4, v239
	v_add_u32_e32 v249, s46, v249
	v_lshlrev_b32_e32 v250, 4, v253
	v_add_u32_e32 v251, 0, v249
	v_lshl_or_b32 v200, v251, 11, v250
	v_lshl_or_b32 v209, v251, 12, v250
	v_add_u32_e32 v251, 4, v249
	v_lshl_or_b32 v201, v251, 11, v250
	v_lshl_or_b32 v210, v251, 12, v250
	v_add_u32_e32 v251, 8, v249
	v_lshl_or_b32 v202, v251, 11, v250
	v_lshl_or_b32 v211, v251, 12, v250
	v_add_u32_e32 v251, 12, v249
	v_lshl_or_b32 v203, v251, 11, v250
	v_lshl_or_b32 v214, v251, 12, v250
	v_add_u32_e32 v251, 16, v249
	v_lshl_or_b32 v204, v251, 11, v250
	v_lshl_or_b32 v215, v251, 12, v250
	v_add_u32_e32 v251, 20, v249
	v_lshl_or_b32 v206, v251, 11, v250
	v_lshl_or_b32 v216, v251, 12, v250
	v_add_u32_e32 v251, 24, v249
	v_lshl_or_b32 v207, v251, 11, v250
	v_lshl_or_b32 v217, v251, 12, v250
	v_add_u32_e32 v251, 28, v249
	v_lshl_or_b32 v208, v251, 11, v250
	v_lshl_or_b32 v219, v251, 12, v250
	s_lshl_b32 s21, s75, 23
	s_lshl_b32 s32, s59, 19
	s_add_u32 s21, s21, s32
	s_lshl_b32 s32, s61, 1
	s_add_u32 s21, s21, s32
	s_add_u32 s21, s21, 0xda00000
	s_add_u32 s0, s8, s21
	s_addc_u32 s1, s9, 0
	s_add_u32 s4, s0, 0x4000000
	s_addc_u32 s5, s1, 0
	s_add_u32 s6, s0, 0x24000000
	s_addc_u32 s7, s1, 0
	global_load_dwordx4 v[0:3], v200, s[0:1] nt
	global_load_dwordx4 v[32:35], v200, s[4:5] nt
	global_load_dwordx4 v[4:7], v201, s[0:1] nt
	global_load_dwordx4 v[36:39], v201, s[4:5] nt
	global_load_dwordx4 v[8:11], v202, s[0:1] nt
	global_load_dwordx4 v[40:43], v202, s[4:5] nt
	global_load_dwordx4 v[12:15], v203, s[0:1] nt
	global_load_dwordx4 v[44:47], v203, s[4:5] nt
	global_load_dwordx4 v[16:19], v204, s[0:1] nt
	global_load_dwordx4 v[48:51], v204, s[4:5] nt
	global_load_dwordx4 v[20:23], v206, s[0:1] nt
	global_load_dwordx4 v[52:55], v206, s[4:5] nt
	global_load_dwordx4 v[24:27], v207, s[0:1] nt
	global_load_dwordx4 v[56:59], v207, s[4:5] nt
	global_load_dwordx4 v[28:31], v208, s[0:1] nt
	global_load_dwordx4 v[60:63], v208, s[4:5] nt
	global_load_dwordx4 v[64:67], v200, s[6:7] nt
	global_load_dwordx4 v[68:71], v201, s[6:7] nt
	global_load_dwordx4 v[72:75], v202, s[6:7] nt
	global_load_dwordx4 v[76:79], v203, s[6:7] nt
	global_load_dwordx4 v[80:83], v204, s[6:7] nt
	global_load_dwordx4 v[84:87], v206, s[6:7] nt
	global_load_dwordx4 v[88:91], v207, s[6:7] nt
	global_load_dwordx4 v[92:95], v208, s[6:7] nt
	v_readlane_b32 s21, v255, 51
	v_mov_b32_e32 v243, 0x20090
	ds_read_b128 v[112:115], v243
	ds_read_b128 v[116:119], v243 offset:16
	ds_read_b64 v[120:121], v243 offset:32
	s_lshl_b32 s32, s21, 6
	v_add_u32_e32 v244, s32, v239
	v_lshlrev_b32_e32 v244, 2, v244
	s_waitcnt lgkmcnt(0)
	v_readfirstlane_b32 s0, v112
	v_readfirstlane_b32 s1, v113
	v_readfirstlane_b32 s4, v114
	v_readfirstlane_b32 s5, v115
	v_readfirstlane_b32 s6, v116
	v_readfirstlane_b32 s7, v117
	v_readfirstlane_b32 s28, v118
	v_readfirstlane_b32 s29, v119
	v_readfirstlane_b32 s54, v120
	v_readfirstlane_b32 s55, v121
	s_lshl_b32 s32, s21, 9
	s_add_u32 s54, s54, s32
	s_addc_u32 s55, s55, 0
	v_lshlrev_b32_e32 v249, 5, v253
	s_nop 3
	global_load_dword v122, v244, s[0:1]
	global_load_dword v123, v244, s[4:5]
	global_load_dword v124, v244, s[6:7]
	global_load_dword v125, v244, s[28:29]
	global_load_dwordx4 v[192:195], v249, s[54:55]
	global_load_dwordx4 v[196:199], v249, s[54:55] offset:16
	v_lshlrev_b32_e32 v252, 2, v239
	s_waitcnt vmcnt(0)
	v_mul_f32_e32 v126, v122, v123
	v_mul_f32_e32 v127, v124, v125
	v_xor_b32_e32 v243, 4, v252
	ds_bpermute_b32 v128, v243, v126
	ds_bpermute_b32 v129, v243, v127
	s_waitcnt lgkmcnt(0)
	v_add_f32_e32 v126, v126, v128
	v_add_f32_e32 v127, v127, v129
	v_xor_b32_e32 v243, 8, v252
	ds_bpermute_b32 v128, v243, v126
	ds_bpermute_b32 v129, v243, v127
	s_waitcnt lgkmcnt(0)
	v_add_f32_e32 v126, v126, v128
	v_add_f32_e32 v127, v127, v129
	v_xor_b32_e32 v243, 16, v252
	ds_bpermute_b32 v128, v243, v126
	ds_bpermute_b32 v129, v243, v127
	s_waitcnt lgkmcnt(0)
	v_add_f32_e32 v126, v126, v128
	v_add_f32_e32 v127, v127, v129
	v_xor_b32_e32 v243, 32, v252
	ds_bpermute_b32 v128, v243, v126
	ds_bpermute_b32 v129, v243, v127
	s_waitcnt lgkmcnt(0)
	v_add_f32_e32 v126, v126, v128
	v_add_f32_e32 v127, v127, v129
	v_xor_b32_e32 v243, 64, v252
	ds_bpermute_b32 v128, v243, v126
	ds_bpermute_b32 v129, v243, v127
	s_waitcnt lgkmcnt(0)
	v_add_f32_e32 v126, v126, v128
	v_add_f32_e32 v127, v127, v129
	v_xor_b32_e32 v243, 128, v252
	ds_bpermute_b32 v128, v243, v126
	ds_bpermute_b32 v129, v243, v127
	s_waitcnt lgkmcnt(0)
; #define GASP __attribute__((address_space(1)))
; __device__ __forceinline__ float bflo(unsigned w) { return __uint_as_float(w << 16); }
; __device__ __forceinline__ float bfhi(unsigned w) { return __uint_as_float(w & 0xffff0000u); }
; __global__ void __launch_bounds__(NWAVES * 64, 2) fwd_kernel(Args args) {
;     ...
;                         const float lambda_init = 0.8f - 0.6f * expf(-0.3f * (float)l);
;                         const float* lq1 = (const float*)ldp(L, 18); const float* lk1 = (const float*)ldp(L, 19); const float* lq2 = (const float*)ldp(L, 20); const float* lk2 = (const float*)ldp(L, 21);
;                         const float d1 = wave_sum(lq1[l * 64 + ln] * lk1[l * 64 + ln], ln), d2 = wave_sum(lq2[l * 64 + ln] * lk2[l * 64 + ln], ln);
;                         const float lam = expf(d1) - expf(d2) + lambda_init;
;                         const int c8 = (ln & 15) * 8, sub = ln >> 4;
;                         const float* sg = (const float*)ldp(L, 22) + (size_t)l * 128 + c8;
;                         const f32x4 sg0 = *(const GASP f32x4*)sg * (1.f - lambda_init), sg1 = *(const GASP f32x4*)(sg + 4) * (1.f - lambda_init);
;                         const size_t r0 = (size_t)b * SEQ + qb * 256 + wave * 32 + sub;
;                         const bf16* O1 = (const bf16*)(w2 + WS_H); const bf16* O2 = O1 + (size_t)NTOK * 1024; const bf16* ZA = (const bf16*)(w2 + WS_ZA); bf16* YCAT = (bf16*)(w2 + WS_A2);
;                         v4u pp[8], qq[8], zz[8];
; #pragma unroll
;                         for (int it = 0; it < 8; ++it) { const size_t off = (r0 + it * 4) * 1024 + h * 128 + c8;
;                             pp[it] = *(const GASP v4u*)(O1 + off); qq[it] = *(const GASP v4u*)(O2 + off);
;                             zz[it] = *(const GASP v4u*)(ZA + off); }
; #pragma unroll
;                         for (int it = 0; it < 8; ++it) { const size_t row = r0 + it * 4; const v4u p = pp[it], q = qq[it], z = zz[it];
;                             float d[8]; float ss = 0.f;
; #pragma unroll
;                             for (int e = 0; e < 4; ++e) { d[2 * e] = bflo(p[e]) - lam * bflo(q[e]); d[2 * e + 1] = bfhi(p[e]) - lam * bfhi(q[e]); ss += d[2 * e] * d[2 * e] + d[2 * e + 1] * d[2 * e + 1]; }
	v_add_f32_e32 v126, v126, v128
	v_add_f32_e32 v127, v127, v129
	v_mul_f32_e32 v130, 0x3fb8aa3b, v126
	v_fma_f32 v132, v126, s91, -v130
	v_rndne_f32_e32 v133, v130
	v_fmac_f32_e32 v132, 0x32a5705f, v126
	v_sub_f32_e32 v130, v130, v133
	v_add_f32_e32 v130, v130, v132
	v_exp_f32_e32 v130, v130
	v_cvt_i32_f32_e32 v132, v133
	v_cmp_ngt_f32_e32 vcc, s40, v126
	v_ldexp_f32 v130, v130, v132
	s_nop 0
	v_cndmask_b32_e32 v130, 0, v130, vcc
	v_cmp_nlt_f32_e32 vcc, s41, v126
	s_nop 1
	v_cndmask_b32_e32 v130, v236, v130, vcc
	v_mul_f32_e32 v131, 0x3fb8aa3b, v127
	v_fma_f32 v132, v127, s91, -v131
	v_rndne_f32_e32 v133, v131
	v_fmac_f32_e32 v132, 0x32a5705f, v127
	v_sub_f32_e32 v131, v131, v133
	v_add_f32_e32 v131, v131, v132
	v_exp_f32_e32 v131, v131
	v_cvt_i32_f32_e32 v132, v133
	v_cmp_ngt_f32_e32 vcc, s40, v127
	v_ldexp_f32 v131, v131, v132
	s_nop 0
	v_cndmask_b32_e32 v131, 0, v131, vcc
	v_cmp_nlt_f32_e32 vcc, s41, v127
	s_nop 1
	v_cndmask_b32_e32 v131, v236, v131, vcc
	v_sub_f32_e32 v130, v130, v131
	v_add_f32_e32 v130, v130, v240
	v_mul_f32_e32 v192, v192, v218
	v_mul_f32_e32 v193, v193, v218
	v_mul_f32_e32 v194, v194, v218
	v_mul_f32_e32 v195, v195, v218
	v_mul_f32_e32 v196, v196, v218
	v_mul_f32_e32 v197, v197, v218
	v_mul_f32_e32 v198, v198, v218
	v_mul_f32_e32 v199, v199, v218
	v_readfirstlane_b32 s26, v130
	s_lshl_b32 s21, s75, 23
	s_lshl_b32 s32, s58, 19
	s_add_u32 s21, s21, s32
	s_lshl_b32 s32, s61, 1
	s_add_u32 s21, s21, s32
	s_add_u32 s21, s21, 0xda00000
	s_add_u32 s0, s8, s21
	s_addc_u32 s1, s9, 0
	s_add_u32 s4, s0, 0x4000000
	s_addc_u32 s5, s1, 0
	s_add_u32 s6, s0, 0x24000000
	s_addc_u32 s7, s1, 0
	global_load_dwordx4 v[96:99], v200, s[0:1] nt
	global_load_dwordx4 v[128:131], v200, s[4:5] nt
	global_load_dwordx4 v[100:103], v201, s[0:1] nt
	global_load_dwordx4 v[132:135], v201, s[4:5] nt
	global_load_dwordx4 v[104:107], v202, s[0:1] nt
	global_load_dwordx4 v[136:139], v202, s[4:5] nt
	global_load_dwordx4 v[108:111], v203, s[0:1] nt
	global_load_dwordx4 v[140:143], v203, s[4:5] nt
	global_load_dwordx4 v[112:115], v204, s[0:1] nt
	global_load_dwordx4 v[144:147], v204, s[4:5] nt
	global_load_dwordx4 v[116:119], v206, s[0:1] nt
	global_load_dwordx4 v[148:151], v206, s[4:5] nt
	global_load_dwordx4 v[120:123], v207, s[0:1] nt
	global_load_dwordx4 v[152:155], v207, s[4:5] nt
	global_load_dwordx4 v[124:127], v208, s[0:1] nt
	global_load_dwordx4 v[156:159], v208, s[4:5] nt
	global_load_dwordx4 v[160:163], v200, s[6:7] nt
	global_load_dwordx4 v[164:167], v201, s[6:7] nt
	global_load_dwordx4 v[168:171], v202, s[6:7] nt
	global_load_dwordx4 v[172:175], v203, s[6:7] nt
	global_load_dwordx4 v[176:179], v204, s[6:7] nt
	global_load_dwordx4 v[180:183], v206, s[6:7] nt
	global_load_dwordx4 v[184:187], v207, s[6:7] nt
	global_load_dwordx4 v[188:191], v208, s[6:7] nt
	s_lshl_b32 s21, s75, 24
	s_lshl_b32 s32, s59, 20
	s_add_u32 s21, s21, s32
	s_lshl_b32 s32, s61, 1
	s_add_u32 s21, s21, s32
	s_add_u32 s21, s21, 0x15a00800
	s_add_u32 s28, s8, s21
	s_addc_u32 s29, s9, 0
	s_waitcnt vmcnt(24)
	v_lshlrev_b32_e32 v249, 16, v32
	v_and_b32_e32 v250, s79, v32
	v_lshlrev_b32_e32 v251, 16, v0
	v_and_b32_e32 v252, s79, v0
	v_fma_f32 v0, -s26, v249, v251
	v_fma_f32 v32, -s26, v250, v252
	v_lshlrev_b32_e32 v249, 16, v33
	v_and_b32_e32 v250, s79, v33
	v_lshlrev_b32_e32 v251, 16, v1
	v_and_b32_e32 v252, s79, v1
	v_mul_f32_e32 v241, v0, v0
	v_mul_f32_e32 v222, v32, v32
	v_fma_f32 v1, -s26, v249, v251
	v_fma_f32 v33, -s26, v250, v252
	v_lshlrev_b32_e32 v249, 16, v34
	v_and_b32_e32 v250, s79, v34
	v_lshlrev_b32_e32 v251, 16, v2
	v_and_b32_e32 v252, s79, v2
	v_fmac_f32_e32 v241, v1, v1
	v_fmac_f32_e32 v222, v33, v33
	v_fma_f32 v2, -s26, v249, v251
	v_fma_f32 v34, -s26, v250, v252
	v_lshlrev_b32_e32 v249, 16, v35
	v_and_b32_e32 v250, s79, v35
	v_lshlrev_b32_e32 v251, 16, v3
	v_and_b32_e32 v252, s79, v3
	v_fmac_f32_e32 v241, v2, v2
	v_fmac_f32_e32 v222, v34, v34
	v_fma_f32 v3, -s26, v249, v251
	v_fma_f32 v35, -s26, v250, v252
	s_nop 0
	v_fmac_f32_e32 v241, v3, v3
	v_fmac_f32_e32 v222, v35, v35
	v_lshlrev_b32_e32 v249, 16, v36
	v_and_b32_e32 v250, s79, v36
	v_lshlrev_b32_e32 v251, 16, v4
	v_and_b32_e32 v252, s79, v4
	v_fma_f32 v4, -s26, v249, v251
	v_fma_f32 v36, -s26, v250, v252
	v_lshlrev_b32_e32 v249, 16, v37
	v_and_b32_e32 v250, s79, v37
	v_lshlrev_b32_e32 v251, 16, v5
	v_and_b32_e32 v252, s79, v5
	v_mul_f32_e32 v242, v4, v4
	v_mul_f32_e32 v223, v36, v36
	v_fma_f32 v5, -s26, v249, v251
	v_fma_f32 v37, -s26, v250, v252
	v_lshlrev_b32_e32 v249, 16, v38
	v_and_b32_e32 v250, s79, v38
	v_lshlrev_b32_e32 v251, 16, v6
	v_and_b32_e32 v252, s79, v6
	v_fmac_f32_e32 v242, v5, v5
	v_fmac_f32_e32 v223, v37, v37
	v_fma_f32 v6, -s26, v249, v251
	v_fma_f32 v38, -s26, v250, v252
	v_lshlrev_b32_e32 v249, 16, v39
	v_and_b32_e32 v250, s79, v39
	v_lshlrev_b32_e32 v251, 16, v7
	v_and_b32_e32 v252, s79, v7
	v_fmac_f32_e32 v242, v6, v6
	v_fmac_f32_e32 v223, v38, v38
	v_fma_f32 v7, -s26, v249, v251
	v_fma_f32 v39, -s26, v250, v252
	s_nop 0
	v_fmac_f32_e32 v242, v7, v7
	v_fmac_f32_e32 v223, v39, v39
	v_lshlrev_b32_e32 v249, 16, v40
	v_and_b32_e32 v250, s79, v40
	v_lshlrev_b32_e32 v251, 16, v8
	v_and_b32_e32 v252, s79, v8
	v_fma_f32 v8, -s26, v249, v251
	v_fma_f32 v40, -s26, v250, v252
	v_lshlrev_b32_e32 v249, 16, v41
	v_and_b32_e32 v250, s79, v41
	v_lshlrev_b32_e32 v251, 16, v9
	v_and_b32_e32 v252, s79, v9
	v_mul_f32_e32 v243, v8, v8
	v_mul_f32_e32 v224, v40, v40
	v_fma_f32 v9, -s26, v249, v251
	v_fma_f32 v41, -s26, v250, v252
	v_lshlrev_b32_e32 v249, 16, v42
	v_and_b32_e32 v250, s79, v42
	v_lshlrev_b32_e32 v251, 16, v10
	v_and_b32_e32 v252, s79, v10
	v_fmac_f32_e32 v243, v9, v9
	v_fmac_f32_e32 v224, v41, v41
; __device__ __forceinline__ float bflo(unsigned w) { return __uint_as_float(w << 16); }
; __device__ __forceinline__ float bfhi(unsigned w) { return __uint_as_float(w & 0xffff0000u); }
; __global__ void __launch_bounds__(NWAVES * 64, 2) fwd_kernel(Args args) {
;     ...
;                         for (int it = 0; it < 8; ++it) { const size_t row = r0 + it * 4; const v4u p = pp[it], q = qq[it], z = zz[it];
;                             float d[8]; float ss = 0.f;
; #pragma unroll
;                             for (int e = 0; e < 4; ++e) { d[2 * e] = bflo(p[e]) - lam * bflo(q[e]); d[2 * e + 1] = bfhi(p[e]) - lam * bfhi(q[e]); ss += d[2 * e] * d[2 * e] + d[2 * e + 1] * d[2 * e + 1]; }
	v_fma_f32 v10, -s26, v249, v251
	v_fma_f32 v42, -s26, v250, v252
	v_lshlrev_b32_e32 v249, 16, v43
	v_and_b32_e32 v250, s79, v43
	v_lshlrev_b32_e32 v251, 16, v11
	v_and_b32_e32 v252, s79, v11
	v_fmac_f32_e32 v243, v10, v10
	v_fmac_f32_e32 v224, v42, v42
	v_fma_f32 v11, -s26, v249, v251
	v_fma_f32 v43, -s26, v250, v252
	s_nop 0
	v_fmac_f32_e32 v243, v11, v11
	v_fmac_f32_e32 v224, v43, v43
	v_lshlrev_b32_e32 v249, 16, v44
	v_and_b32_e32 v250, s79, v44
	v_lshlrev_b32_e32 v251, 16, v12
	v_and_b32_e32 v252, s79, v12
	v_fma_f32 v12, -s26, v249, v251
	v_fma_f32 v44, -s26, v250, v252
	v_lshlrev_b32_e32 v249, 16, v45
	v_and_b32_e32 v250, s79, v45
	v_lshlrev_b32_e32 v251, 16, v13
	v_and_b32_e32 v252, s79, v13
	v_mul_f32_e32 v244, v12, v12
	v_mul_f32_e32 v225, v44, v44
	v_fma_f32 v13, -s26, v249, v251
	v_fma_f32 v45, -s26, v250, v252
	v_lshlrev_b32_e32 v249, 16, v46
	v_and_b32_e32 v250, s79, v46
	v_lshlrev_b32_e32 v251, 16, v14
	v_and_b32_e32 v252, s79, v14
	v_fmac_f32_e32 v244, v13, v13
	v_fmac_f32_e32 v225, v45, v45
	v_fma_f32 v14, -s26, v249, v251
	v_fma_f32 v46, -s26, v250, v252
	v_lshlrev_b32_e32 v249, 16, v47
	v_and_b32_e32 v250, s79, v47
	v_lshlrev_b32_e32 v251, 16, v15
	v_and_b32_e32 v252, s79, v15
	v_fmac_f32_e32 v244, v14, v14
	v_fmac_f32_e32 v225, v46, v46
	v_fma_f32 v15, -s26, v249, v251
	v_fma_f32 v47, -s26, v250, v252
	s_nop 0
	v_fmac_f32_e32 v244, v15, v15
	v_fmac_f32_e32 v225, v47, v47
	v_lshlrev_b32_e32 v249, 16, v48
	v_and_b32_e32 v250, s79, v48
	v_lshlrev_b32_e32 v251, 16, v16
	v_and_b32_e32 v252, s79, v16
	v_fma_f32 v16, -s26, v249, v251
	v_fma_f32 v48, -s26, v250, v252
	v_lshlrev_b32_e32 v249, 16, v49
	v_and_b32_e32 v250, s79, v49
	v_lshlrev_b32_e32 v251, 16, v17
	v_and_b32_e32 v252, s79, v17
	v_mul_f32_e32 v245, v16, v16
	v_mul_f32_e32 v226, v48, v48
	v_fma_f32 v17, -s26, v249, v251
	v_fma_f32 v49, -s26, v250, v252
	v_lshlrev_b32_e32 v249, 16, v50
	v_and_b32_e32 v250, s79, v50
	v_lshlrev_b32_e32 v251, 16, v18
	v_and_b32_e32 v252, s79, v18
	v_fmac_f32_e32 v245, v17, v17
	v_fmac_f32_e32 v226, v49, v49
	v_fma_f32 v18, -s26, v249, v251
	v_fma_f32 v50, -s26, v250, v252
	v_lshlrev_b32_e32 v249, 16, v51
	v_and_b32_e32 v250, s79, v51
	v_lshlrev_b32_e32 v251, 16, v19
	v_and_b32_e32 v252, s79, v19
	v_fmac_f32_e32 v245, v18, v18
	v_fmac_f32_e32 v226, v50, v50
	v_fma_f32 v19, -s26, v249, v251
	v_fma_f32 v51, -s26, v250, v252
	s_nop 0
	v_fmac_f32_e32 v245, v19, v19
	v_fmac_f32_e32 v226, v51, v51
	v_lshlrev_b32_e32 v249, 16, v52
	v_and_b32_e32 v250, s79, v52
	v_lshlrev_b32_e32 v251, 16, v20
	v_and_b32_e32 v252, s79, v20
	v_fma_f32 v20, -s26, v249, v251
	v_fma_f32 v52, -s26, v250, v252
	v_lshlrev_b32_e32 v249, 16, v53
	v_and_b32_e32 v250, s79, v53
	v_lshlrev_b32_e32 v251, 16, v21
	v_and_b32_e32 v252, s79, v21
	v_mul_f32_e32 v246, v20, v20
	v_mul_f32_e32 v227, v52, v52
	v_fma_f32 v21, -s26, v249, v251
	v_fma_f32 v53, -s26, v250, v252
	v_lshlrev_b32_e32 v249, 16, v54
	v_and_b32_e32 v250, s79, v54
	v_lshlrev_b32_e32 v251, 16, v22
	v_and_b32_e32 v252, s79, v22
	v_fmac_f32_e32 v246, v21, v21
	v_fmac_f32_e32 v227, v53, v53
	v_fma_f32 v22, -s26, v249, v251
	v_fma_f32 v54, -s26, v250, v252
	v_lshlrev_b32_e32 v249, 16, v55
	v_and_b32_e32 v250, s79, v55
	v_lshlrev_b32_e32 v251, 16, v23
	v_and_b32_e32 v252, s79, v23
	v_fmac_f32_e32 v246, v22, v22
	v_fmac_f32_e32 v227, v54, v54
	v_fma_f32 v23, -s26, v249, v251
	v_fma_f32 v55, -s26, v250, v252
	s_nop 0
	v_fmac_f32_e32 v246, v23, v23
	v_fmac_f32_e32 v227, v55, v55
	v_lshlrev_b32_e32 v249, 16, v56
	v_and_b32_e32 v250, s79, v56
	v_lshlrev_b32_e32 v251, 16, v24
	v_and_b32_e32 v252, s79, v24
	v_fma_f32 v24, -s26, v249, v251
	v_fma_f32 v56, -s26, v250, v252
	v_lshlrev_b32_e32 v249, 16, v57
	v_and_b32_e32 v250, s79, v57
	v_lshlrev_b32_e32 v251, 16, v25
	v_and_b32_e32 v252, s79, v25
	v_mul_f32_e32 v247, v24, v24
	v_mul_f32_e32 v228, v56, v56
	v_fma_f32 v25, -s26, v249, v251
	v_fma_f32 v57, -s26, v250, v252
	v_lshlrev_b32_e32 v249, 16, v58
	v_and_b32_e32 v250, s79, v58
	v_lshlrev_b32_e32 v251, 16, v26
	v_and_b32_e32 v252, s79, v26
	v_fmac_f32_e32 v247, v25, v25
	v_fmac_f32_e32 v228, v57, v57
	v_fma_f32 v26, -s26, v249, v251
	v_fma_f32 v58, -s26, v250, v252
	v_lshlrev_b32_e32 v249, 16, v59
	v_and_b32_e32 v250, s79, v59
	v_lshlrev_b32_e32 v251, 16, v27
	v_and_b32_e32 v252, s79, v27
	v_fmac_f32_e32 v247, v26, v26
	v_fmac_f32_e32 v228, v58, v58
	v_fma_f32 v27, -s26, v249, v251
	v_fma_f32 v59, -s26, v250, v252
	s_nop 0
	v_fmac_f32_e32 v247, v27, v27
	v_fmac_f32_e32 v228, v59, v59
	v_lshlrev_b32_e32 v249, 16, v60
	v_and_b32_e32 v250, s79, v60
	v_lshlrev_b32_e32 v251, 16, v28
	v_and_b32_e32 v252, s79, v28
	v_fma_f32 v28, -s26, v249, v251
	v_fma_f32 v60, -s26, v250, v252
	v_lshlrev_b32_e32 v249, 16, v61
	v_and_b32_e32 v250, s79, v61
	v_lshlrev_b32_e32 v251, 16, v29
	v_and_b32_e32 v252, s79, v29
	v_mul_f32_e32 v248, v28, v28
	v_mul_f32_e32 v229, v60, v60
	v_fma_f32 v29, -s26, v249, v251
	v_fma_f32 v61, -s26, v250, v252
	v_lshlrev_b32_e32 v249, 16, v62
	v_and_b32_e32 v250, s79, v62
	v_lshlrev_b32_e32 v251, 16, v30
	v_and_b32_e32 v252, s79, v30
	v_fmac_f32_e32 v248, v29, v29
	v_fmac_f32_e32 v229, v61, v61
	v_fma_f32 v30, -s26, v249, v251
	v_fma_f32 v62, -s26, v250, v252
	v_lshlrev_b32_e32 v249, 16, v63
	v_and_b32_e32 v250, s79, v63
	v_lshlrev_b32_e32 v251, 16, v31
	v_and_b32_e32 v252, s79, v31
	v_fmac_f32_e32 v248, v30, v30
	v_fmac_f32_e32 v229, v62, v62
	v_fma_f32 v31, -s26, v249, v251
	v_fma_f32 v63, -s26, v250, v252
	s_nop 0
	v_fmac_f32_e32 v248, v31, v31
	v_fmac_f32_e32 v229, v63, v63
	v_add_f32_e32 v241, v241, v222
	v_add_f32_e32 v242, v242, v223
	v_add_f32_e32 v243, v243, v224
	v_add_f32_e32 v244, v244, v225
; #define GASP __attribute__((address_space(1)))
; __device__ __forceinline__ float lane_xor(float v, int lane, int o) { return __int_as_float(__builtin_amdgcn_ds_bpermute((lane ^ o) << 2, __float_as_int(v))); }
; __device__ __forceinline__ unsigned pk2(float lo, float hi) { return f2bf(lo) | (f2bf(hi) << 16); }
; __device__ __forceinline__ float bflo(unsigned w) { return __uint_as_float(w << 16); }
; __device__ __forceinline__ float bfhi(unsigned w) { return __uint_as_float(w & 0xffff0000u); }
; __global__ void __launch_bounds__(NWAVES * 64, 2) fwd_kernel(Args args) {
;     ...
;                         for (int it = 0; it < 8; ++it) { const size_t row = r0 + it * 4; const v4u p = pp[it], q = qq[it], z = zz[it];
;                             float d[8]; float ss = 0.f;
; #pragma unroll
;                             for (int e = 0; e < 4; ++e) { d[2 * e] = bflo(p[e]) - lam * bflo(q[e]); d[2 * e + 1] = bfhi(p[e]) - lam * bfhi(q[e]); ss += d[2 * e] * d[2 * e] + d[2 * e + 1] * d[2 * e + 1]; }
;                             ss += lane_xor(ss, ln, 1); ss += lane_xor(ss, ln, 2); ss += lane_xor(ss, ln, 4); ss += lane_xor(ss, ln, 8);
;                             const float r = 1.0f / sqrtf(ss * (1.f / 128.f) + 1e-6f);
;                             v4u o;
;                             o[0] = pk2(d[0] * r * sg0[0] * bflo(z[0]), d[1] * r * sg0[1] * bfhi(z[0])); o[1] = pk2(d[2] * r * sg0[2] * bflo(z[1]), d[3] * r * sg0[3] * bfhi(z[1]));
;                             o[2] = pk2(d[4] * r * sg1[0] * bflo(z[2]), d[5] * r * sg1[1] * bfhi(z[2])); o[3] = pk2(d[6] * r * sg1[2] * bflo(z[3]), d[7] * r * sg1[3] * bfhi(z[3]));
;                             *(GASP v4u*)(YCAT + row * 2048 + 1024 + h * 128 + c8) = o; }
	v_add_f32_e32 v245, v245, v226
	v_add_f32_e32 v246, v246, v227
	v_add_f32_e32 v247, v247, v228
	v_add_f32_e32 v248, v248, v229
	v_add_f32_dpp v241, v241, v241 quad_perm:[1,0,3,2] row_mask:0xf bank_mask:0xf
	v_add_f32_dpp v242, v242, v242 quad_perm:[1,0,3,2] row_mask:0xf bank_mask:0xf
	v_add_f32_dpp v243, v243, v243 quad_perm:[1,0,3,2] row_mask:0xf bank_mask:0xf
	v_add_f32_dpp v244, v244, v244 quad_perm:[1,0,3,2] row_mask:0xf bank_mask:0xf
	v_add_f32_dpp v245, v245, v245 quad_perm:[1,0,3,2] row_mask:0xf bank_mask:0xf
	v_add_f32_dpp v246, v246, v246 quad_perm:[1,0,3,2] row_mask:0xf bank_mask:0xf
	v_add_f32_dpp v247, v247, v247 quad_perm:[1,0,3,2] row_mask:0xf bank_mask:0xf
	v_add_f32_dpp v248, v248, v248 quad_perm:[1,0,3,2] row_mask:0xf bank_mask:0xf
	v_add_f32_dpp v241, v241, v241 quad_perm:[2,3,0,1] row_mask:0xf bank_mask:0xf
	v_add_f32_dpp v242, v242, v242 quad_perm:[2,3,0,1] row_mask:0xf bank_mask:0xf
	v_add_f32_dpp v243, v243, v243 quad_perm:[2,3,0,1] row_mask:0xf bank_mask:0xf
	v_add_f32_dpp v244, v244, v244 quad_perm:[2,3,0,1] row_mask:0xf bank_mask:0xf
	v_add_f32_dpp v245, v245, v245 quad_perm:[2,3,0,1] row_mask:0xf bank_mask:0xf
	v_add_f32_dpp v246, v246, v246 quad_perm:[2,3,0,1] row_mask:0xf bank_mask:0xf
	v_add_f32_dpp v247, v247, v247 quad_perm:[2,3,0,1] row_mask:0xf bank_mask:0xf
	v_add_f32_dpp v248, v248, v248 quad_perm:[2,3,0,1] row_mask:0xf bank_mask:0xf
	v_add_f32_dpp v241, v241, v241 row_ror:4 row_mask:0xf bank_mask:0xf
	v_add_f32_dpp v242, v242, v242 row_ror:4 row_mask:0xf bank_mask:0xf
	v_add_f32_dpp v243, v243, v243 row_ror:4 row_mask:0xf bank_mask:0xf
	v_add_f32_dpp v244, v244, v244 row_ror:4 row_mask:0xf bank_mask:0xf
	v_add_f32_dpp v245, v245, v245 row_ror:4 row_mask:0xf bank_mask:0xf
	v_add_f32_dpp v246, v246, v246 row_ror:4 row_mask:0xf bank_mask:0xf
	v_add_f32_dpp v247, v247, v247 row_ror:4 row_mask:0xf bank_mask:0xf
	v_add_f32_dpp v248, v248, v248 row_ror:4 row_mask:0xf bank_mask:0xf
	v_add_f32_dpp v241, v241, v241 row_ror:8 row_mask:0xf bank_mask:0xf
	v_add_f32_dpp v242, v242, v242 row_ror:8 row_mask:0xf bank_mask:0xf
	v_add_f32_dpp v243, v243, v243 row_ror:8 row_mask:0xf bank_mask:0xf
	v_add_f32_dpp v244, v244, v244 row_ror:8 row_mask:0xf bank_mask:0xf
	v_add_f32_dpp v245, v245, v245 row_ror:8 row_mask:0xf bank_mask:0xf
	v_add_f32_dpp v246, v246, v246 row_ror:8 row_mask:0xf bank_mask:0xf
	v_add_f32_dpp v247, v247, v247 row_ror:8 row_mask:0xf bank_mask:0xf
	v_add_f32_dpp v248, v248, v248 row_ror:8 row_mask:0xf bank_mask:0xf
	v_fmamk_f32 v241, v241, 0x3c000000, v231
	v_fmamk_f32 v242, v242, 0x3c000000, v231
	v_fmamk_f32 v243, v243, 0x3c000000, v231
	v_fmamk_f32 v244, v244, 0x3c000000, v231
	v_fmamk_f32 v245, v245, 0x3c000000, v231
	v_fmamk_f32 v246, v246, 0x3c000000, v231
	v_fmamk_f32 v247, v247, 0x3c000000, v231
	v_fmamk_f32 v248, v248, 0x3c000000, v231
	v_rsq_f32_e32 v241, v241
	v_rsq_f32_e32 v242, v242
	v_rsq_f32_e32 v243, v243
	v_rsq_f32_e32 v244, v244
	v_rsq_f32_e32 v245, v245
	v_rsq_f32_e32 v246, v246
	v_rsq_f32_e32 v247, v247
	v_rsq_f32_e32 v248, v248
	v_lshlrev_b32_e32 v249, 16, v64
	v_and_b32_e32 v250, s79, v64
	v_mul_f32_e32 v0, v0, v241
	v_mul_f32_e32 v32, v32, v241
	v_mul_f32_e32 v0, v0, v192
	v_mul_f32_e32 v32, v32, v193
	v_mul_f32_e32 v0, v0, v249
	v_mul_f32_e32 v32, v32, v250
	v_cvt_pk_bf16_f32 v64, v0, v32
	v_lshlrev_b32_e32 v251, 16, v65
	v_and_b32_e32 v252, s79, v65
	v_mul_f32_e32 v1, v1, v241
	v_mul_f32_e32 v33, v33, v241
	v_mul_f32_e32 v1, v1, v194
	v_mul_f32_e32 v33, v33, v195
	v_mul_f32_e32 v1, v1, v251
	v_mul_f32_e32 v33, v33, v252
	v_cvt_pk_bf16_f32 v65, v1, v33
	v_lshlrev_b32_e32 v249, 16, v66
	v_and_b32_e32 v250, s79, v66
	v_mul_f32_e32 v2, v2, v241
	v_mul_f32_e32 v34, v34, v241
	v_mul_f32_e32 v2, v2, v196
	v_mul_f32_e32 v34, v34, v197
	v_mul_f32_e32 v2, v2, v249
	v_mul_f32_e32 v34, v34, v250
	v_cvt_pk_bf16_f32 v66, v2, v34
	v_lshlrev_b32_e32 v251, 16, v67
	v_and_b32_e32 v252, s79, v67
	v_mul_f32_e32 v3, v3, v241
	v_mul_f32_e32 v35, v35, v241
	v_mul_f32_e32 v3, v3, v198
	v_mul_f32_e32 v35, v35, v199
	v_mul_f32_e32 v3, v3, v251
	v_mul_f32_e32 v35, v35, v252
	v_cvt_pk_bf16_f32 v67, v3, v35
	global_store_dwordx4 v209, v[64:67], s[28:29] nt
	v_lshlrev_b32_e32 v249, 16, v68
	v_and_b32_e32 v250, s79, v68
	v_mul_f32_e32 v4, v4, v242
	v_mul_f32_e32 v36, v36, v242
	v_mul_f32_e32 v4, v4, v192
	v_mul_f32_e32 v36, v36, v193
	v_mul_f32_e32 v4, v4, v249
	v_mul_f32_e32 v36, v36, v250
	v_cvt_pk_bf16_f32 v68, v4, v36
	v_lshlrev_b32_e32 v251, 16, v69
	v_and_b32_e32 v252, s79, v69
	v_mul_f32_e32 v5, v5, v242
	v_mul_f32_e32 v37, v37, v242
	v_mul_f32_e32 v5, v5, v194
	v_mul_f32_e32 v37, v37, v195
	v_mul_f32_e32 v5, v5, v251
	v_mul_f32_e32 v37, v37, v252
	v_cvt_pk_bf16_f32 v69, v5, v37
	v_lshlrev_b32_e32 v249, 16, v70
	v_and_b32_e32 v250, s79, v70
	v_mul_f32_e32 v6, v6, v242
	v_mul_f32_e32 v38, v38, v242
	v_mul_f32_e32 v6, v6, v196
	v_mul_f32_e32 v38, v38, v197
	v_mul_f32_e32 v6, v6, v249
	v_mul_f32_e32 v38, v38, v250
	v_cvt_pk_bf16_f32 v70, v6, v38
	v_lshlrev_b32_e32 v251, 16, v71
	v_and_b32_e32 v252, s79, v71
	v_mul_f32_e32 v7, v7, v242
	v_mul_f32_e32 v39, v39, v242
	v_mul_f32_e32 v7, v7, v198
	v_mul_f32_e32 v39, v39, v199
	v_mul_f32_e32 v7, v7, v251
	v_mul_f32_e32 v39, v39, v252
	v_cvt_pk_bf16_f32 v71, v7, v39
	global_store_dwordx4 v210, v[68:71], s[28:29] nt
	v_lshlrev_b32_e32 v249, 16, v72
	v_and_b32_e32 v250, s79, v72
	v_mul_f32_e32 v8, v8, v243
	v_mul_f32_e32 v40, v40, v243
	v_mul_f32_e32 v8, v8, v192
	v_mul_f32_e32 v40, v40, v193
	v_mul_f32_e32 v8, v8, v249
	v_mul_f32_e32 v40, v40, v250
	v_cvt_pk_bf16_f32 v72, v8, v40
	v_lshlrev_b32_e32 v251, 16, v73
	v_and_b32_e32 v252, s79, v73
	v_mul_f32_e32 v9, v9, v243
; #define GASP __attribute__((address_space(1)))
; __device__ __forceinline__ float lane_xor(float v, int lane, int o) { return __int_as_float(__builtin_amdgcn_ds_bpermute((lane ^ o) << 2, __float_as_int(v))); }
; __device__ __forceinline__ unsigned pk2(float lo, float hi) { return f2bf(lo) | (f2bf(hi) << 16); }
; __device__ __forceinline__ float bflo(unsigned w) { return __uint_as_float(w << 16); }
; __device__ __forceinline__ float bfhi(unsigned w) { return __uint_as_float(w & 0xffff0000u); }
; __global__ void __launch_bounds__(NWAVES * 64, 2) fwd_kernel(Args args) {
;     ...
;                             for (int e = 0; e < 4; ++e) { d[2 * e] = bflo(p[e]) - lam * bflo(q[e]); d[2 * e + 1] = bfhi(p[e]) - lam * bfhi(q[e]); ss += d[2 * e] * d[2 * e] + d[2 * e + 1] * d[2 * e + 1]; }
;                             ss += lane_xor(ss, ln, 1); ss += lane_xor(ss, ln, 2); ss += lane_xor(ss, ln, 4); ss += lane_xor(ss, ln, 8);
;                             const float r = 1.0f / sqrtf(ss * (1.f / 128.f) + 1e-6f);
;                             v4u o;
;                             o[0] = pk2(d[0] * r * sg0[0] * bflo(z[0]), d[1] * r * sg0[1] * bfhi(z[0])); o[1] = pk2(d[2] * r * sg0[2] * bflo(z[1]), d[3] * r * sg0[3] * bfhi(z[1]));
;                             o[2] = pk2(d[4] * r * sg1[0] * bflo(z[2]), d[5] * r * sg1[1] * bfhi(z[2])); o[3] = pk2(d[6] * r * sg1[2] * bflo(z[3]), d[7] * r * sg1[3] * bfhi(z[3]));
;                             *(GASP v4u*)(YCAT + row * 2048 + 1024 + h * 128 + c8) = o; }
	v_mul_f32_e32 v41, v41, v243
	v_mul_f32_e32 v9, v9, v194
	v_mul_f32_e32 v41, v41, v195
	v_mul_f32_e32 v9, v9, v251
	v_mul_f32_e32 v41, v41, v252
	v_cvt_pk_bf16_f32 v73, v9, v41
	v_lshlrev_b32_e32 v249, 16, v74
	v_and_b32_e32 v250, s79, v74
	v_mul_f32_e32 v10, v10, v243
	v_mul_f32_e32 v42, v42, v243
	v_mul_f32_e32 v10, v10, v196
	v_mul_f32_e32 v42, v42, v197
	v_mul_f32_e32 v10, v10, v249
	v_mul_f32_e32 v42, v42, v250
	v_cvt_pk_bf16_f32 v74, v10, v42
	v_lshlrev_b32_e32 v251, 16, v75
	v_and_b32_e32 v252, s79, v75
	v_mul_f32_e32 v11, v11, v243
	v_mul_f32_e32 v43, v43, v243
	v_mul_f32_e32 v11, v11, v198
	v_mul_f32_e32 v43, v43, v199
	v_mul_f32_e32 v11, v11, v251
	v_mul_f32_e32 v43, v43, v252
	v_cvt_pk_bf16_f32 v75, v11, v43
	global_store_dwordx4 v211, v[72:75], s[28:29] nt
	v_lshlrev_b32_e32 v249, 16, v76
	v_and_b32_e32 v250, s79, v76
	v_mul_f32_e32 v12, v12, v244
	v_mul_f32_e32 v44, v44, v244
	v_mul_f32_e32 v12, v12, v192
	v_mul_f32_e32 v44, v44, v193
	v_mul_f32_e32 v12, v12, v249
	v_mul_f32_e32 v44, v44, v250
	v_cvt_pk_bf16_f32 v76, v12, v44
	v_lshlrev_b32_e32 v251, 16, v77
	v_and_b32_e32 v252, s79, v77
	v_mul_f32_e32 v13, v13, v244
	v_mul_f32_e32 v45, v45, v244
	v_mul_f32_e32 v13, v13, v194
	v_mul_f32_e32 v45, v45, v195
	v_mul_f32_e32 v13, v13, v251
	v_mul_f32_e32 v45, v45, v252
	v_cvt_pk_bf16_f32 v77, v13, v45
	v_lshlrev_b32_e32 v249, 16, v78
	v_and_b32_e32 v250, s79, v78
	v_mul_f32_e32 v14, v14, v244
	v_mul_f32_e32 v46, v46, v244
	v_mul_f32_e32 v14, v14, v196
	v_mul_f32_e32 v46, v46, v197
	v_mul_f32_e32 v14, v14, v249
	v_mul_f32_e32 v46, v46, v250
	v_cvt_pk_bf16_f32 v78, v14, v46
	v_lshlrev_b32_e32 v251, 16, v79
	v_and_b32_e32 v252, s79, v79
	v_mul_f32_e32 v15, v15, v244
	v_mul_f32_e32 v47, v47, v244
	v_mul_f32_e32 v15, v15, v198
	v_mul_f32_e32 v47, v47, v199
	v_mul_f32_e32 v15, v15, v251
	v_mul_f32_e32 v47, v47, v252
	v_cvt_pk_bf16_f32 v79, v15, v47
	global_store_dwordx4 v214, v[76:79], s[28:29] nt
	v_lshlrev_b32_e32 v249, 16, v80
	v_and_b32_e32 v250, s79, v80
	v_mul_f32_e32 v16, v16, v245
	v_mul_f32_e32 v48, v48, v245
	v_mul_f32_e32 v16, v16, v192
	v_mul_f32_e32 v48, v48, v193
	v_mul_f32_e32 v16, v16, v249
	v_mul_f32_e32 v48, v48, v250
	v_cvt_pk_bf16_f32 v80, v16, v48
	v_lshlrev_b32_e32 v251, 16, v81
	v_and_b32_e32 v252, s79, v81
	v_mul_f32_e32 v17, v17, v245
	v_mul_f32_e32 v49, v49, v245
	v_mul_f32_e32 v17, v17, v194
	v_mul_f32_e32 v49, v49, v195
	v_mul_f32_e32 v17, v17, v251
	v_mul_f32_e32 v49, v49, v252
	v_cvt_pk_bf16_f32 v81, v17, v49
	v_lshlrev_b32_e32 v249, 16, v82
	v_and_b32_e32 v250, s79, v82
	v_mul_f32_e32 v18, v18, v245
	v_mul_f32_e32 v50, v50, v245
	v_mul_f32_e32 v18, v18, v196
	v_mul_f32_e32 v50, v50, v197
	v_mul_f32_e32 v18, v18, v249
	v_mul_f32_e32 v50, v50, v250
	v_cvt_pk_bf16_f32 v82, v18, v50
	v_lshlrev_b32_e32 v251, 16, v83
	v_and_b32_e32 v252, s79, v83
	v_mul_f32_e32 v19, v19, v245
	v_mul_f32_e32 v51, v51, v245
	v_mul_f32_e32 v19, v19, v198
	v_mul_f32_e32 v51, v51, v199
	v_mul_f32_e32 v19, v19, v251
	v_mul_f32_e32 v51, v51, v252
	v_cvt_pk_bf16_f32 v83, v19, v51
	global_store_dwordx4 v215, v[80:83], s[28:29] nt
	v_lshlrev_b32_e32 v249, 16, v84
	v_and_b32_e32 v250, s79, v84
	v_mul_f32_e32 v20, v20, v246
	v_mul_f32_e32 v52, v52, v246
	v_mul_f32_e32 v20, v20, v192
	v_mul_f32_e32 v52, v52, v193
	v_mul_f32_e32 v20, v20, v249
	v_mul_f32_e32 v52, v52, v250
	v_cvt_pk_bf16_f32 v84, v20, v52
	v_lshlrev_b32_e32 v251, 16, v85
	v_and_b32_e32 v252, s79, v85
	v_mul_f32_e32 v21, v21, v246
	v_mul_f32_e32 v53, v53, v246
	v_mul_f32_e32 v21, v21, v194
	v_mul_f32_e32 v53, v53, v195
	v_mul_f32_e32 v21, v21, v251
	v_mul_f32_e32 v53, v53, v252
	v_cvt_pk_bf16_f32 v85, v21, v53
	v_lshlrev_b32_e32 v249, 16, v86
	v_and_b32_e32 v250, s79, v86
	v_mul_f32_e32 v22, v22, v246
	v_mul_f32_e32 v54, v54, v246
	v_mul_f32_e32 v22, v22, v196
	v_mul_f32_e32 v54, v54, v197
	v_mul_f32_e32 v22, v22, v249
	v_mul_f32_e32 v54, v54, v250
	v_cvt_pk_bf16_f32 v86, v22, v54
	v_lshlrev_b32_e32 v251, 16, v87
	v_and_b32_e32 v252, s79, v87
	v_mul_f32_e32 v23, v23, v246
	v_mul_f32_e32 v55, v55, v246
	v_mul_f32_e32 v23, v23, v198
	v_mul_f32_e32 v55, v55, v199
	v_mul_f32_e32 v23, v23, v251
	v_mul_f32_e32 v55, v55, v252
	v_cvt_pk_bf16_f32 v87, v23, v55
	global_store_dwordx4 v216, v[84:87], s[28:29] nt
	v_lshlrev_b32_e32 v249, 16, v88
	v_and_b32_e32 v250, s79, v88
	v_mul_f32_e32 v24, v24, v247
	v_mul_f32_e32 v56, v56, v247
	v_mul_f32_e32 v24, v24, v192
	v_mul_f32_e32 v56, v56, v193
	v_mul_f32_e32 v24, v24, v249
	v_mul_f32_e32 v56, v56, v250
	v_cvt_pk_bf16_f32 v88, v24, v56
	v_lshlrev_b32_e32 v251, 16, v89
	v_and_b32_e32 v252, s79, v89
	v_mul_f32_e32 v25, v25, v247
	v_mul_f32_e32 v57, v57, v247
	v_mul_f32_e32 v25, v25, v194
	v_mul_f32_e32 v57, v57, v195
	v_mul_f32_e32 v25, v25, v251
	v_mul_f32_e32 v57, v57, v252
	v_cvt_pk_bf16_f32 v89, v25, v57
	v_lshlrev_b32_e32 v249, 16, v90
	v_and_b32_e32 v250, s79, v90
	v_mul_f32_e32 v26, v26, v247
	v_mul_f32_e32 v58, v58, v247
	v_mul_f32_e32 v26, v26, v196
	v_mul_f32_e32 v58, v58, v197
	v_mul_f32_e32 v26, v26, v249
	v_mul_f32_e32 v58, v58, v250
	v_cvt_pk_bf16_f32 v90, v26, v58
	v_lshlrev_b32_e32 v251, 16, v91
	v_and_b32_e32 v252, s79, v91
	v_mul_f32_e32 v27, v27, v247
	v_mul_f32_e32 v59, v59, v247
	v_mul_f32_e32 v27, v27, v198
	v_mul_f32_e32 v59, v59, v199
	v_mul_f32_e32 v27, v27, v251
	v_mul_f32_e32 v59, v59, v252
	v_cvt_pk_bf16_f32 v91, v27, v59
	global_store_dwordx4 v217, v[88:91], s[28:29] nt
	v_lshlrev_b32_e32 v249, 16, v92
	v_and_b32_e32 v250, s79, v92
	v_mul_f32_e32 v28, v28, v248
	v_mul_f32_e32 v60, v60, v248
	v_mul_f32_e32 v28, v28, v192
	v_mul_f32_e32 v60, v60, v193
	v_mul_f32_e32 v28, v28, v249
	v_mul_f32_e32 v60, v60, v250
; #define GASP __attribute__((address_space(1)))
; __device__ __forceinline__ unsigned pk2(float lo, float hi) { return f2bf(lo) | (f2bf(hi) << 16); }
; __device__ __forceinline__ float bflo(unsigned w) { return __uint_as_float(w << 16); }
; __device__ __forceinline__ float bfhi(unsigned w) { return __uint_as_float(w & 0xffff0000u); }
; __global__ void __launch_bounds__(NWAVES * 64, 2) fwd_kernel(Args args) {
;     ...
;                         for (int it = 0; it < 8; ++it) { const size_t off = (r0 + it * 4) * 1024 + h * 128 + c8;
;                             pp[it] = *(const GASP v4u*)(O1 + off); qq[it] = *(const GASP v4u*)(O2 + off);
;                             zz[it] = *(const GASP v4u*)(ZA + off); }
; #pragma unroll
;                         for (int it = 0; it < 8; ++it) { const size_t row = r0 + it * 4; const v4u p = pp[it], q = qq[it], z = zz[it];
;                             float d[8]; float ss = 0.f;
; #pragma unroll
;                             for (int e = 0; e < 4; ++e) { d[2 * e] = bflo(p[e]) - lam * bflo(q[e]); d[2 * e + 1] = bfhi(p[e]) - lam * bfhi(q[e]); ss += d[2 * e] * d[2 * e] + d[2 * e + 1] * d[2 * e + 1]; }
;     ...
;                             o[0] = pk2(d[0] * r * sg0[0] * bflo(z[0]), d[1] * r * sg0[1] * bfhi(z[0])); o[1] = pk2(d[2] * r * sg0[2] * bflo(z[1]), d[3] * r * sg0[3] * bfhi(z[1]));
;                             o[2] = pk2(d[4] * r * sg1[0] * bflo(z[2]), d[5] * r * sg1[1] * bfhi(z[2])); o[3] = pk2(d[6] * r * sg1[2] * bflo(z[3]), d[7] * r * sg1[3] * bfhi(z[3]));
;                             *(GASP v4u*)(YCAT + row * 2048 + 1024 + h * 128 + c8) = o; }
	v_cvt_pk_bf16_f32 v92, v28, v60
	v_lshlrev_b32_e32 v251, 16, v93
	v_and_b32_e32 v252, s79, v93
	v_mul_f32_e32 v29, v29, v248
	v_mul_f32_e32 v61, v61, v248
	v_mul_f32_e32 v29, v29, v194
	v_mul_f32_e32 v61, v61, v195
	v_mul_f32_e32 v29, v29, v251
	v_mul_f32_e32 v61, v61, v252
	v_cvt_pk_bf16_f32 v93, v29, v61
	v_lshlrev_b32_e32 v249, 16, v94
	v_and_b32_e32 v250, s79, v94
	v_mul_f32_e32 v30, v30, v248
	v_mul_f32_e32 v62, v62, v248
	v_mul_f32_e32 v30, v30, v196
	v_mul_f32_e32 v62, v62, v197
	v_mul_f32_e32 v30, v30, v249
	v_mul_f32_e32 v62, v62, v250
	v_cvt_pk_bf16_f32 v94, v30, v62
	v_lshlrev_b32_e32 v251, 16, v95
	v_and_b32_e32 v252, s79, v95
	v_mul_f32_e32 v31, v31, v248
	v_mul_f32_e32 v63, v63, v248
	v_mul_f32_e32 v31, v31, v198
	v_mul_f32_e32 v63, v63, v199
	v_mul_f32_e32 v31, v31, v251
	v_mul_f32_e32 v63, v63, v252
	v_cvt_pk_bf16_f32 v95, v31, v63
	global_store_dwordx4 v219, v[92:95], s[28:29] nt
	s_lshl_b32 s21, s75, 23
	s_lshl_b32 s32, s60, 19
	s_add_u32 s21, s21, s32
	s_lshl_b32 s32, s61, 1
	s_add_u32 s21, s21, s32
	s_add_u32 s21, s21, 0xda00000
	s_add_u32 s0, s8, s21
	s_addc_u32 s1, s9, 0
	s_add_u32 s4, s0, 0x4000000
	s_addc_u32 s5, s1, 0
	s_add_u32 s6, s0, 0x24000000
	s_addc_u32 s7, s1, 0
	global_load_dwordx4 v[0:3], v200, s[0:1] nt
	global_load_dwordx4 v[32:35], v200, s[4:5] nt
	global_load_dwordx4 v[4:7], v201, s[0:1] nt
	global_load_dwordx4 v[36:39], v201, s[4:5] nt
	global_load_dwordx4 v[8:11], v202, s[0:1] nt
	global_load_dwordx4 v[40:43], v202, s[4:5] nt
	global_load_dwordx4 v[12:15], v203, s[0:1] nt
	global_load_dwordx4 v[44:47], v203, s[4:5] nt
	global_load_dwordx4 v[16:19], v204, s[0:1] nt
	global_load_dwordx4 v[48:51], v204, s[4:5] nt
	global_load_dwordx4 v[20:23], v206, s[0:1] nt
	global_load_dwordx4 v[52:55], v206, s[4:5] nt
	global_load_dwordx4 v[24:27], v207, s[0:1] nt
	global_load_dwordx4 v[56:59], v207, s[4:5] nt
	global_load_dwordx4 v[28:31], v208, s[0:1] nt
	global_load_dwordx4 v[60:63], v208, s[4:5] nt
	global_load_dwordx4 v[64:67], v200, s[6:7] nt
	global_load_dwordx4 v[68:71], v201, s[6:7] nt
	global_load_dwordx4 v[72:75], v202, s[6:7] nt
	global_load_dwordx4 v[76:79], v203, s[6:7] nt
	global_load_dwordx4 v[80:83], v204, s[6:7] nt
	global_load_dwordx4 v[84:87], v206, s[6:7] nt
	global_load_dwordx4 v[88:91], v207, s[6:7] nt
	global_load_dwordx4 v[92:95], v208, s[6:7] nt
	s_lshl_b32 s21, s75, 24
	s_lshl_b32 s32, s58, 20
	s_add_u32 s21, s21, s32
	s_lshl_b32 s32, s61, 1
	s_add_u32 s21, s21, s32
	s_add_u32 s21, s21, 0x15a00800
	s_add_u32 s28, s8, s21
	s_addc_u32 s29, s9, 0
	s_waitcnt vmcnt(32)
	v_lshlrev_b32_e32 v249, 16, v128
	v_and_b32_e32 v250, s79, v128
	v_lshlrev_b32_e32 v251, 16, v96
	v_and_b32_e32 v252, s79, v96
	v_fma_f32 v96, -s26, v249, v251
	v_fma_f32 v128, -s26, v250, v252
	v_lshlrev_b32_e32 v249, 16, v129
	v_and_b32_e32 v250, s79, v129
	v_lshlrev_b32_e32 v251, 16, v97
	v_and_b32_e32 v252, s79, v97
	v_mul_f32_e32 v241, v96, v96
	v_mul_f32_e32 v222, v128, v128
	v_fma_f32 v97, -s26, v249, v251
	v_fma_f32 v129, -s26, v250, v252
	v_lshlrev_b32_e32 v249, 16, v130
	v_and_b32_e32 v250, s79, v130
	v_lshlrev_b32_e32 v251, 16, v98
	v_and_b32_e32 v252, s79, v98
	v_fmac_f32_e32 v241, v97, v97
	v_fmac_f32_e32 v222, v129, v129
	v_fma_f32 v98, -s26, v249, v251
	v_fma_f32 v130, -s26, v250, v252
	v_lshlrev_b32_e32 v249, 16, v131
	v_and_b32_e32 v250, s79, v131
	v_lshlrev_b32_e32 v251, 16, v99
	v_and_b32_e32 v252, s79, v99
	v_fmac_f32_e32 v241, v98, v98
	v_fmac_f32_e32 v222, v130, v130
	v_fma_f32 v99, -s26, v249, v251
	v_fma_f32 v131, -s26, v250, v252
	s_nop 0
	v_fmac_f32_e32 v241, v99, v99
	v_fmac_f32_e32 v222, v131, v131
	v_lshlrev_b32_e32 v249, 16, v132
	v_and_b32_e32 v250, s79, v132
	v_lshlrev_b32_e32 v251, 16, v100
	v_and_b32_e32 v252, s79, v100
	v_fma_f32 v100, -s26, v249, v251
	v_fma_f32 v132, -s26, v250, v252
	v_lshlrev_b32_e32 v249, 16, v133
	v_and_b32_e32 v250, s79, v133
	v_lshlrev_b32_e32 v251, 16, v101
	v_and_b32_e32 v252, s79, v101
	v_mul_f32_e32 v242, v100, v100
	v_mul_f32_e32 v223, v132, v132
	v_fma_f32 v101, -s26, v249, v251
	v_fma_f32 v133, -s26, v250, v252
	v_lshlrev_b32_e32 v249, 16, v134
	v_and_b32_e32 v250, s79, v134
	v_lshlrev_b32_e32 v251, 16, v102
	v_and_b32_e32 v252, s79, v102
	v_fmac_f32_e32 v242, v101, v101
	v_fmac_f32_e32 v223, v133, v133
	v_fma_f32 v102, -s26, v249, v251
	v_fma_f32 v134, -s26, v250, v252
	v_lshlrev_b32_e32 v249, 16, v135
	v_and_b32_e32 v250, s79, v135
	v_lshlrev_b32_e32 v251, 16, v103
	v_and_b32_e32 v252, s79, v103
	v_fmac_f32_e32 v242, v102, v102
	v_fmac_f32_e32 v223, v134, v134
	v_fma_f32 v103, -s26, v249, v251
	v_fma_f32 v135, -s26, v250, v252
	s_nop 0
	v_fmac_f32_e32 v242, v103, v103
	v_fmac_f32_e32 v223, v135, v135
	v_lshlrev_b32_e32 v249, 16, v136
	v_and_b32_e32 v250, s79, v136
	v_lshlrev_b32_e32 v251, 16, v104
	v_and_b32_e32 v252, s79, v104
	v_fma_f32 v104, -s26, v249, v251
	v_fma_f32 v136, -s26, v250, v252
	v_lshlrev_b32_e32 v249, 16, v137
	v_and_b32_e32 v250, s79, v137
	v_lshlrev_b32_e32 v251, 16, v105
	v_and_b32_e32 v252, s79, v105
	v_mul_f32_e32 v243, v104, v104
	v_mul_f32_e32 v224, v136, v136
	v_fma_f32 v105, -s26, v249, v251
	v_fma_f32 v137, -s26, v250, v252
	v_lshlrev_b32_e32 v249, 16, v138
	v_and_b32_e32 v250, s79, v138
	v_lshlrev_b32_e32 v251, 16, v106
	v_and_b32_e32 v252, s79, v106
	v_fmac_f32_e32 v243, v105, v105
	v_fmac_f32_e32 v224, v137, v137
	v_fma_f32 v106, -s26, v249, v251
	v_fma_f32 v138, -s26, v250, v252
	v_lshlrev_b32_e32 v249, 16, v139
	v_and_b32_e32 v250, s79, v139
	v_lshlrev_b32_e32 v251, 16, v107
	v_and_b32_e32 v252, s79, v107
	v_fmac_f32_e32 v243, v106, v106
	v_fmac_f32_e32 v224, v138, v138
	v_fma_f32 v107, -s26, v249, v251
	v_fma_f32 v139, -s26, v250, v252
; __device__ __forceinline__ float bflo(unsigned w) { return __uint_as_float(w << 16); }
; __device__ __forceinline__ float bfhi(unsigned w) { return __uint_as_float(w & 0xffff0000u); }
; __global__ void __launch_bounds__(NWAVES * 64, 2) fwd_kernel(Args args) {
;     ...
;                         for (int it = 0; it < 8; ++it) { const size_t row = r0 + it * 4; const v4u p = pp[it], q = qq[it], z = zz[it];
;                             float d[8]; float ss = 0.f;
; #pragma unroll
;                             for (int e = 0; e < 4; ++e) { d[2 * e] = bflo(p[e]) - lam * bflo(q[e]); d[2 * e + 1] = bfhi(p[e]) - lam * bfhi(q[e]); ss += d[2 * e] * d[2 * e] + d[2 * e + 1] * d[2 * e + 1]; }
	s_nop 0
	v_fmac_f32_e32 v243, v107, v107
	v_fmac_f32_e32 v224, v139, v139
	v_lshlrev_b32_e32 v249, 16, v140
	v_and_b32_e32 v250, s79, v140
	v_lshlrev_b32_e32 v251, 16, v108
	v_and_b32_e32 v252, s79, v108
	v_fma_f32 v108, -s26, v249, v251
	v_fma_f32 v140, -s26, v250, v252
	v_lshlrev_b32_e32 v249, 16, v141
	v_and_b32_e32 v250, s79, v141
	v_lshlrev_b32_e32 v251, 16, v109
	v_and_b32_e32 v252, s79, v109
	v_mul_f32_e32 v244, v108, v108
	v_mul_f32_e32 v225, v140, v140
	v_fma_f32 v109, -s26, v249, v251
	v_fma_f32 v141, -s26, v250, v252
	v_lshlrev_b32_e32 v249, 16, v142
	v_and_b32_e32 v250, s79, v142
	v_lshlrev_b32_e32 v251, 16, v110
	v_and_b32_e32 v252, s79, v110
	v_fmac_f32_e32 v244, v109, v109
	v_fmac_f32_e32 v225, v141, v141
	v_fma_f32 v110, -s26, v249, v251
	v_fma_f32 v142, -s26, v250, v252
	v_lshlrev_b32_e32 v249, 16, v143
	v_and_b32_e32 v250, s79, v143
	v_lshlrev_b32_e32 v251, 16, v111
	v_and_b32_e32 v252, s79, v111
	v_fmac_f32_e32 v244, v110, v110
	v_fmac_f32_e32 v225, v142, v142
	v_fma_f32 v111, -s26, v249, v251
	v_fma_f32 v143, -s26, v250, v252
	s_nop 0
	v_fmac_f32_e32 v244, v111, v111
	v_fmac_f32_e32 v225, v143, v143
	v_lshlrev_b32_e32 v249, 16, v144
	v_and_b32_e32 v250, s79, v144
	v_lshlrev_b32_e32 v251, 16, v112
	v_and_b32_e32 v252, s79, v112
	v_fma_f32 v112, -s26, v249, v251
	v_fma_f32 v144, -s26, v250, v252
	v_lshlrev_b32_e32 v249, 16, v145
	v_and_b32_e32 v250, s79, v145
	v_lshlrev_b32_e32 v251, 16, v113
	v_and_b32_e32 v252, s79, v113
	v_mul_f32_e32 v245, v112, v112
	v_mul_f32_e32 v226, v144, v144
	v_fma_f32 v113, -s26, v249, v251
	v_fma_f32 v145, -s26, v250, v252
	v_lshlrev_b32_e32 v249, 16, v146
	v_and_b32_e32 v250, s79, v146
	v_lshlrev_b32_e32 v251, 16, v114
	v_and_b32_e32 v252, s79, v114
	v_fmac_f32_e32 v245, v113, v113
	v_fmac_f32_e32 v226, v145, v145
	v_fma_f32 v114, -s26, v249, v251
	v_fma_f32 v146, -s26, v250, v252
	v_lshlrev_b32_e32 v249, 16, v147
	v_and_b32_e32 v250, s79, v147
	v_lshlrev_b32_e32 v251, 16, v115
	v_and_b32_e32 v252, s79, v115
	v_fmac_f32_e32 v245, v114, v114
	v_fmac_f32_e32 v226, v146, v146
	v_fma_f32 v115, -s26, v249, v251
	v_fma_f32 v147, -s26, v250, v252
	s_nop 0
	v_fmac_f32_e32 v245, v115, v115
	v_fmac_f32_e32 v226, v147, v147
	v_lshlrev_b32_e32 v249, 16, v148
	v_and_b32_e32 v250, s79, v148
	v_lshlrev_b32_e32 v251, 16, v116
	v_and_b32_e32 v252, s79, v116
	v_fma_f32 v116, -s26, v249, v251
	v_fma_f32 v148, -s26, v250, v252
	v_lshlrev_b32_e32 v249, 16, v149
	v_and_b32_e32 v250, s79, v149
	v_lshlrev_b32_e32 v251, 16, v117
	v_and_b32_e32 v252, s79, v117
	v_mul_f32_e32 v246, v116, v116
	v_mul_f32_e32 v227, v148, v148
	v_fma_f32 v117, -s26, v249, v251
	v_fma_f32 v149, -s26, v250, v252
	v_lshlrev_b32_e32 v249, 16, v150
	v_and_b32_e32 v250, s79, v150
	v_lshlrev_b32_e32 v251, 16, v118
	v_and_b32_e32 v252, s79, v118
	v_fmac_f32_e32 v246, v117, v117
	v_fmac_f32_e32 v227, v149, v149
	v_fma_f32 v118, -s26, v249, v251
	v_fma_f32 v150, -s26, v250, v252
	v_lshlrev_b32_e32 v249, 16, v151
	v_and_b32_e32 v250, s79, v151
	v_lshlrev_b32_e32 v251, 16, v119
	v_and_b32_e32 v252, s79, v119
	v_fmac_f32_e32 v246, v118, v118
	v_fmac_f32_e32 v227, v150, v150
	v_fma_f32 v119, -s26, v249, v251
	v_fma_f32 v151, -s26, v250, v252
	s_nop 0
	v_fmac_f32_e32 v246, v119, v119
	v_fmac_f32_e32 v227, v151, v151
	v_lshlrev_b32_e32 v249, 16, v152
	v_and_b32_e32 v250, s79, v152
	v_lshlrev_b32_e32 v251, 16, v120
	v_and_b32_e32 v252, s79, v120
	v_fma_f32 v120, -s26, v249, v251
	v_fma_f32 v152, -s26, v250, v252
	v_lshlrev_b32_e32 v249, 16, v153
	v_and_b32_e32 v250, s79, v153
	v_lshlrev_b32_e32 v251, 16, v121
	v_and_b32_e32 v252, s79, v121
	v_mul_f32_e32 v247, v120, v120
	v_mul_f32_e32 v228, v152, v152
	v_fma_f32 v121, -s26, v249, v251
	v_fma_f32 v153, -s26, v250, v252
	v_lshlrev_b32_e32 v249, 16, v154
	v_and_b32_e32 v250, s79, v154
	v_lshlrev_b32_e32 v251, 16, v122
	v_and_b32_e32 v252, s79, v122
	v_fmac_f32_e32 v247, v121, v121
	v_fmac_f32_e32 v228, v153, v153
	v_fma_f32 v122, -s26, v249, v251
	v_fma_f32 v154, -s26, v250, v252
	v_lshlrev_b32_e32 v249, 16, v155
	v_and_b32_e32 v250, s79, v155
	v_lshlrev_b32_e32 v251, 16, v123
	v_and_b32_e32 v252, s79, v123
	v_fmac_f32_e32 v247, v122, v122
	v_fmac_f32_e32 v228, v154, v154
	v_fma_f32 v123, -s26, v249, v251
	v_fma_f32 v155, -s26, v250, v252
	s_nop 0
	v_fmac_f32_e32 v247, v123, v123
	v_fmac_f32_e32 v228, v155, v155
	v_lshlrev_b32_e32 v249, 16, v156
	v_and_b32_e32 v250, s79, v156
	v_lshlrev_b32_e32 v251, 16, v124
	v_and_b32_e32 v252, s79, v124
	v_fma_f32 v124, -s26, v249, v251
	v_fma_f32 v156, -s26, v250, v252
	v_lshlrev_b32_e32 v249, 16, v157
	v_and_b32_e32 v250, s79, v157
	v_lshlrev_b32_e32 v251, 16, v125
	v_and_b32_e32 v252, s79, v125
	v_mul_f32_e32 v248, v124, v124
	v_mul_f32_e32 v229, v156, v156
	v_fma_f32 v125, -s26, v249, v251
	v_fma_f32 v157, -s26, v250, v252
	v_lshlrev_b32_e32 v249, 16, v158
	v_and_b32_e32 v250, s79, v158
	v_lshlrev_b32_e32 v251, 16, v126
	v_and_b32_e32 v252, s79, v126
	v_fmac_f32_e32 v248, v125, v125
	v_fmac_f32_e32 v229, v157, v157
	v_fma_f32 v126, -s26, v249, v251
	v_fma_f32 v158, -s26, v250, v252
	v_lshlrev_b32_e32 v249, 16, v159
	v_and_b32_e32 v250, s79, v159
	v_lshlrev_b32_e32 v251, 16, v127
	v_and_b32_e32 v252, s79, v127
	v_fmac_f32_e32 v248, v126, v126
	v_fmac_f32_e32 v229, v158, v158
	v_fma_f32 v127, -s26, v249, v251
	v_fma_f32 v159, -s26, v250, v252
	s_nop 0
	v_fmac_f32_e32 v248, v127, v127
	v_fmac_f32_e32 v229, v159, v159
	v_add_f32_e32 v241, v241, v222
	v_add_f32_e32 v242, v242, v223
	v_add_f32_e32 v243, v243, v224
	v_add_f32_e32 v244, v244, v225
	v_add_f32_e32 v245, v245, v226
	v_add_f32_e32 v246, v246, v227
	v_add_f32_e32 v247, v247, v228
	v_add_f32_e32 v248, v248, v229
; #define GASP __attribute__((address_space(1)))
; __device__ __forceinline__ float lane_xor(float v, int lane, int o) { return __int_as_float(__builtin_amdgcn_ds_bpermute((lane ^ o) << 2, __float_as_int(v))); }
; __device__ __forceinline__ unsigned pk2(float lo, float hi) { return f2bf(lo) | (f2bf(hi) << 16); }
; __device__ __forceinline__ float bflo(unsigned w) { return __uint_as_float(w << 16); }
; __device__ __forceinline__ float bfhi(unsigned w) { return __uint_as_float(w & 0xffff0000u); }
; __global__ void __launch_bounds__(NWAVES * 64, 2) fwd_kernel(Args args) {
;     ...
;                             ss += lane_xor(ss, ln, 1); ss += lane_xor(ss, ln, 2); ss += lane_xor(ss, ln, 4); ss += lane_xor(ss, ln, 8);
;                             const float r = 1.0f / sqrtf(ss * (1.f / 128.f) + 1e-6f);
;                             v4u o;
;                             o[0] = pk2(d[0] * r * sg0[0] * bflo(z[0]), d[1] * r * sg0[1] * bfhi(z[0])); o[1] = pk2(d[2] * r * sg0[2] * bflo(z[1]), d[3] * r * sg0[3] * bfhi(z[1]));
;                             o[2] = pk2(d[4] * r * sg1[0] * bflo(z[2]), d[5] * r * sg1[1] * bfhi(z[2])); o[3] = pk2(d[6] * r * sg1[2] * bflo(z[3]), d[7] * r * sg1[3] * bfhi(z[3]));
;                             *(GASP v4u*)(YCAT + row * 2048 + 1024 + h * 128 + c8) = o; }
	v_add_f32_dpp v241, v241, v241 quad_perm:[1,0,3,2] row_mask:0xf bank_mask:0xf
	v_add_f32_dpp v242, v242, v242 quad_perm:[1,0,3,2] row_mask:0xf bank_mask:0xf
	v_add_f32_dpp v243, v243, v243 quad_perm:[1,0,3,2] row_mask:0xf bank_mask:0xf
	v_add_f32_dpp v244, v244, v244 quad_perm:[1,0,3,2] row_mask:0xf bank_mask:0xf
	v_add_f32_dpp v245, v245, v245 quad_perm:[1,0,3,2] row_mask:0xf bank_mask:0xf
	v_add_f32_dpp v246, v246, v246 quad_perm:[1,0,3,2] row_mask:0xf bank_mask:0xf
	v_add_f32_dpp v247, v247, v247 quad_perm:[1,0,3,2] row_mask:0xf bank_mask:0xf
	v_add_f32_dpp v248, v248, v248 quad_perm:[1,0,3,2] row_mask:0xf bank_mask:0xf
	v_add_f32_dpp v241, v241, v241 quad_perm:[2,3,0,1] row_mask:0xf bank_mask:0xf
	v_add_f32_dpp v242, v242, v242 quad_perm:[2,3,0,1] row_mask:0xf bank_mask:0xf
	v_add_f32_dpp v243, v243, v243 quad_perm:[2,3,0,1] row_mask:0xf bank_mask:0xf
	v_add_f32_dpp v244, v244, v244 quad_perm:[2,3,0,1] row_mask:0xf bank_mask:0xf
	v_add_f32_dpp v245, v245, v245 quad_perm:[2,3,0,1] row_mask:0xf bank_mask:0xf
	v_add_f32_dpp v246, v246, v246 quad_perm:[2,3,0,1] row_mask:0xf bank_mask:0xf
	v_add_f32_dpp v247, v247, v247 quad_perm:[2,3,0,1] row_mask:0xf bank_mask:0xf
	v_add_f32_dpp v248, v248, v248 quad_perm:[2,3,0,1] row_mask:0xf bank_mask:0xf
	v_add_f32_dpp v241, v241, v241 row_ror:4 row_mask:0xf bank_mask:0xf
	v_add_f32_dpp v242, v242, v242 row_ror:4 row_mask:0xf bank_mask:0xf
	v_add_f32_dpp v243, v243, v243 row_ror:4 row_mask:0xf bank_mask:0xf
	v_add_f32_dpp v244, v244, v244 row_ror:4 row_mask:0xf bank_mask:0xf
	v_add_f32_dpp v245, v245, v245 row_ror:4 row_mask:0xf bank_mask:0xf
	v_add_f32_dpp v246, v246, v246 row_ror:4 row_mask:0xf bank_mask:0xf
	v_add_f32_dpp v247, v247, v247 row_ror:4 row_mask:0xf bank_mask:0xf
	v_add_f32_dpp v248, v248, v248 row_ror:4 row_mask:0xf bank_mask:0xf
	v_add_f32_dpp v241, v241, v241 row_ror:8 row_mask:0xf bank_mask:0xf
	v_add_f32_dpp v242, v242, v242 row_ror:8 row_mask:0xf bank_mask:0xf
	v_add_f32_dpp v243, v243, v243 row_ror:8 row_mask:0xf bank_mask:0xf
	v_add_f32_dpp v244, v244, v244 row_ror:8 row_mask:0xf bank_mask:0xf
	v_add_f32_dpp v245, v245, v245 row_ror:8 row_mask:0xf bank_mask:0xf
	v_add_f32_dpp v246, v246, v246 row_ror:8 row_mask:0xf bank_mask:0xf
	v_add_f32_dpp v247, v247, v247 row_ror:8 row_mask:0xf bank_mask:0xf
	v_add_f32_dpp v248, v248, v248 row_ror:8 row_mask:0xf bank_mask:0xf
	v_fmamk_f32 v241, v241, 0x3c000000, v231
	v_fmamk_f32 v242, v242, 0x3c000000, v231
	v_fmamk_f32 v243, v243, 0x3c000000, v231
	v_fmamk_f32 v244, v244, 0x3c000000, v231
	v_fmamk_f32 v245, v245, 0x3c000000, v231
	v_fmamk_f32 v246, v246, 0x3c000000, v231
	v_fmamk_f32 v247, v247, 0x3c000000, v231
	v_fmamk_f32 v248, v248, 0x3c000000, v231
	v_rsq_f32_e32 v241, v241
	v_rsq_f32_e32 v242, v242
	v_rsq_f32_e32 v243, v243
	v_rsq_f32_e32 v244, v244
	v_rsq_f32_e32 v245, v245
	v_rsq_f32_e32 v246, v246
	v_rsq_f32_e32 v247, v247
	v_rsq_f32_e32 v248, v248
	v_lshlrev_b32_e32 v249, 16, v160
	v_and_b32_e32 v250, s79, v160
	v_mul_f32_e32 v96, v96, v241
	v_mul_f32_e32 v128, v128, v241
	v_mul_f32_e32 v96, v96, v192
	v_mul_f32_e32 v128, v128, v193
	v_mul_f32_e32 v96, v96, v249
	v_mul_f32_e32 v128, v128, v250
	v_cvt_pk_bf16_f32 v160, v96, v128
	v_lshlrev_b32_e32 v251, 16, v161
	v_and_b32_e32 v252, s79, v161
	v_mul_f32_e32 v97, v97, v241
	v_mul_f32_e32 v129, v129, v241
	v_mul_f32_e32 v97, v97, v194
	v_mul_f32_e32 v129, v129, v195
	v_mul_f32_e32 v97, v97, v251
	v_mul_f32_e32 v129, v129, v252
	v_cvt_pk_bf16_f32 v161, v97, v129
	v_lshlrev_b32_e32 v249, 16, v162
	v_and_b32_e32 v250, s79, v162
	v_mul_f32_e32 v98, v98, v241
	v_mul_f32_e32 v130, v130, v241
	v_mul_f32_e32 v98, v98, v196
	v_mul_f32_e32 v130, v130, v197
	v_mul_f32_e32 v98, v98, v249
	v_mul_f32_e32 v130, v130, v250
	v_cvt_pk_bf16_f32 v162, v98, v130
	v_lshlrev_b32_e32 v251, 16, v163
	v_and_b32_e32 v252, s79, v163
	v_mul_f32_e32 v99, v99, v241
	v_mul_f32_e32 v131, v131, v241
	v_mul_f32_e32 v99, v99, v198
	v_mul_f32_e32 v131, v131, v199
	v_mul_f32_e32 v99, v99, v251
	v_mul_f32_e32 v131, v131, v252
	v_cvt_pk_bf16_f32 v163, v99, v131
	global_store_dwordx4 v209, v[160:163], s[28:29] nt
	v_lshlrev_b32_e32 v249, 16, v164
	v_and_b32_e32 v250, s79, v164
	v_mul_f32_e32 v100, v100, v242
	v_mul_f32_e32 v132, v132, v242
	v_mul_f32_e32 v100, v100, v192
	v_mul_f32_e32 v132, v132, v193
	v_mul_f32_e32 v100, v100, v249
	v_mul_f32_e32 v132, v132, v250
	v_cvt_pk_bf16_f32 v164, v100, v132
	v_lshlrev_b32_e32 v251, 16, v165
	v_and_b32_e32 v252, s79, v165
	v_mul_f32_e32 v101, v101, v242
	v_mul_f32_e32 v133, v133, v242
	v_mul_f32_e32 v101, v101, v194
	v_mul_f32_e32 v133, v133, v195
	v_mul_f32_e32 v101, v101, v251
	v_mul_f32_e32 v133, v133, v252
	v_cvt_pk_bf16_f32 v165, v101, v133
	v_lshlrev_b32_e32 v249, 16, v166
	v_and_b32_e32 v250, s79, v166
	v_mul_f32_e32 v102, v102, v242
	v_mul_f32_e32 v134, v134, v242
	v_mul_f32_e32 v102, v102, v196
	v_mul_f32_e32 v134, v134, v197
	v_mul_f32_e32 v102, v102, v249
	v_mul_f32_e32 v134, v134, v250
	v_cvt_pk_bf16_f32 v166, v102, v134
	v_lshlrev_b32_e32 v251, 16, v167
	v_and_b32_e32 v252, s79, v167
	v_mul_f32_e32 v103, v103, v242
	v_mul_f32_e32 v135, v135, v242
	v_mul_f32_e32 v103, v103, v198
	v_mul_f32_e32 v135, v135, v199
	v_mul_f32_e32 v103, v103, v251
	v_mul_f32_e32 v135, v135, v252
	v_cvt_pk_bf16_f32 v167, v103, v135
	global_store_dwordx4 v210, v[164:167], s[28:29] nt
	v_lshlrev_b32_e32 v249, 16, v168
	v_and_b32_e32 v250, s79, v168
	v_mul_f32_e32 v104, v104, v243
	v_mul_f32_e32 v136, v136, v243
	v_mul_f32_e32 v104, v104, v192
	v_mul_f32_e32 v136, v136, v193
	v_mul_f32_e32 v104, v104, v249
	v_mul_f32_e32 v136, v136, v250
	v_cvt_pk_bf16_f32 v168, v104, v136
; #define GASP __attribute__((address_space(1)))
; __device__ __forceinline__ unsigned pk2(float lo, float hi) { return f2bf(lo) | (f2bf(hi) << 16); }
; __device__ __forceinline__ float bflo(unsigned w) { return __uint_as_float(w << 16); }
; __device__ __forceinline__ float bfhi(unsigned w) { return __uint_as_float(w & 0xffff0000u); }
; __global__ void __launch_bounds__(NWAVES * 64, 2) fwd_kernel(Args args) {
;     ...
;                             o[0] = pk2(d[0] * r * sg0[0] * bflo(z[0]), d[1] * r * sg0[1] * bfhi(z[0])); o[1] = pk2(d[2] * r * sg0[2] * bflo(z[1]), d[3] * r * sg0[3] * bfhi(z[1]));
;                             o[2] = pk2(d[4] * r * sg1[0] * bflo(z[2]), d[5] * r * sg1[1] * bfhi(z[2])); o[3] = pk2(d[6] * r * sg1[2] * bflo(z[3]), d[7] * r * sg1[3] * bfhi(z[3]));
;                             *(GASP v4u*)(YCAT + row * 2048 + 1024 + h * 128 + c8) = o; }
	v_lshlrev_b32_e32 v251, 16, v169
	v_and_b32_e32 v252, s79, v169
	v_mul_f32_e32 v105, v105, v243
	v_mul_f32_e32 v137, v137, v243
	v_mul_f32_e32 v105, v105, v194
	v_mul_f32_e32 v137, v137, v195
	v_mul_f32_e32 v105, v105, v251
	v_mul_f32_e32 v137, v137, v252
	v_cvt_pk_bf16_f32 v169, v105, v137
	v_lshlrev_b32_e32 v249, 16, v170
	v_and_b32_e32 v250, s79, v170
	v_mul_f32_e32 v106, v106, v243
	v_mul_f32_e32 v138, v138, v243
	v_mul_f32_e32 v106, v106, v196
	v_mul_f32_e32 v138, v138, v197
	v_mul_f32_e32 v106, v106, v249
	v_mul_f32_e32 v138, v138, v250
	v_cvt_pk_bf16_f32 v170, v106, v138
	v_lshlrev_b32_e32 v251, 16, v171
	v_and_b32_e32 v252, s79, v171
	v_mul_f32_e32 v107, v107, v243
	v_mul_f32_e32 v139, v139, v243
	v_mul_f32_e32 v107, v107, v198
	v_mul_f32_e32 v139, v139, v199
	v_mul_f32_e32 v107, v107, v251
	v_mul_f32_e32 v139, v139, v252
	v_cvt_pk_bf16_f32 v171, v107, v139
	global_store_dwordx4 v211, v[168:171], s[28:29] nt
	v_lshlrev_b32_e32 v249, 16, v172
	v_and_b32_e32 v250, s79, v172
	v_mul_f32_e32 v108, v108, v244
	v_mul_f32_e32 v140, v140, v244
	v_mul_f32_e32 v108, v108, v192
	v_mul_f32_e32 v140, v140, v193
	v_mul_f32_e32 v108, v108, v249
	v_mul_f32_e32 v140, v140, v250
	v_cvt_pk_bf16_f32 v172, v108, v140
	v_lshlrev_b32_e32 v251, 16, v173
	v_and_b32_e32 v252, s79, v173
	v_mul_f32_e32 v109, v109, v244
	v_mul_f32_e32 v141, v141, v244
	v_mul_f32_e32 v109, v109, v194
	v_mul_f32_e32 v141, v141, v195
	v_mul_f32_e32 v109, v109, v251
	v_mul_f32_e32 v141, v141, v252
	v_cvt_pk_bf16_f32 v173, v109, v141
	v_lshlrev_b32_e32 v249, 16, v174
	v_and_b32_e32 v250, s79, v174
	v_mul_f32_e32 v110, v110, v244
	v_mul_f32_e32 v142, v142, v244
	v_mul_f32_e32 v110, v110, v196
	v_mul_f32_e32 v142, v142, v197
	v_mul_f32_e32 v110, v110, v249
	v_mul_f32_e32 v142, v142, v250
	v_cvt_pk_bf16_f32 v174, v110, v142
	v_lshlrev_b32_e32 v251, 16, v175
	v_and_b32_e32 v252, s79, v175
	v_mul_f32_e32 v111, v111, v244
	v_mul_f32_e32 v143, v143, v244
	v_mul_f32_e32 v111, v111, v198
	v_mul_f32_e32 v143, v143, v199
	v_mul_f32_e32 v111, v111, v251
	v_mul_f32_e32 v143, v143, v252
	v_cvt_pk_bf16_f32 v175, v111, v143
	global_store_dwordx4 v214, v[172:175], s[28:29] nt
	v_lshlrev_b32_e32 v249, 16, v176
	v_and_b32_e32 v250, s79, v176
	v_mul_f32_e32 v112, v112, v245
	v_mul_f32_e32 v144, v144, v245
	v_mul_f32_e32 v112, v112, v192
	v_mul_f32_e32 v144, v144, v193
	v_mul_f32_e32 v112, v112, v249
	v_mul_f32_e32 v144, v144, v250
	v_cvt_pk_bf16_f32 v176, v112, v144
	v_lshlrev_b32_e32 v251, 16, v177
	v_and_b32_e32 v252, s79, v177
	v_mul_f32_e32 v113, v113, v245
	v_mul_f32_e32 v145, v145, v245
	v_mul_f32_e32 v113, v113, v194
	v_mul_f32_e32 v145, v145, v195
	v_mul_f32_e32 v113, v113, v251
	v_mul_f32_e32 v145, v145, v252
	v_cvt_pk_bf16_f32 v177, v113, v145
	v_lshlrev_b32_e32 v249, 16, v178
	v_and_b32_e32 v250, s79, v178
	v_mul_f32_e32 v114, v114, v245
	v_mul_f32_e32 v146, v146, v245
	v_mul_f32_e32 v114, v114, v196
	v_mul_f32_e32 v146, v146, v197
	v_mul_f32_e32 v114, v114, v249
	v_mul_f32_e32 v146, v146, v250
	v_cvt_pk_bf16_f32 v178, v114, v146
	v_lshlrev_b32_e32 v251, 16, v179
	v_and_b32_e32 v252, s79, v179
	v_mul_f32_e32 v115, v115, v245
	v_mul_f32_e32 v147, v147, v245
	v_mul_f32_e32 v115, v115, v198
	v_mul_f32_e32 v147, v147, v199
	v_mul_f32_e32 v115, v115, v251
	v_mul_f32_e32 v147, v147, v252
	v_cvt_pk_bf16_f32 v179, v115, v147
	global_store_dwordx4 v215, v[176:179], s[28:29] nt
	v_lshlrev_b32_e32 v249, 16, v180
	v_and_b32_e32 v250, s79, v180
	v_mul_f32_e32 v116, v116, v246
	v_mul_f32_e32 v148, v148, v246
	v_mul_f32_e32 v116, v116, v192
	v_mul_f32_e32 v148, v148, v193
	v_mul_f32_e32 v116, v116, v249
	v_mul_f32_e32 v148, v148, v250
	v_cvt_pk_bf16_f32 v180, v116, v148
	v_lshlrev_b32_e32 v251, 16, v181
	v_and_b32_e32 v252, s79, v181
	v_mul_f32_e32 v117, v117, v246
	v_mul_f32_e32 v149, v149, v246
	v_mul_f32_e32 v117, v117, v194
	v_mul_f32_e32 v149, v149, v195
	v_mul_f32_e32 v117, v117, v251
	v_mul_f32_e32 v149, v149, v252
	v_cvt_pk_bf16_f32 v181, v117, v149
	v_lshlrev_b32_e32 v249, 16, v182
	v_and_b32_e32 v250, s79, v182
	v_mul_f32_e32 v118, v118, v246
	v_mul_f32_e32 v150, v150, v246
	v_mul_f32_e32 v118, v118, v196
	v_mul_f32_e32 v150, v150, v197
	v_mul_f32_e32 v118, v118, v249
	v_mul_f32_e32 v150, v150, v250
	v_cvt_pk_bf16_f32 v182, v118, v150
	v_lshlrev_b32_e32 v251, 16, v183
	v_and_b32_e32 v252, s79, v183
	v_mul_f32_e32 v119, v119, v246
	v_mul_f32_e32 v151, v151, v246
	v_mul_f32_e32 v119, v119, v198
	v_mul_f32_e32 v151, v151, v199
	v_mul_f32_e32 v119, v119, v251
	v_mul_f32_e32 v151, v151, v252
	v_cvt_pk_bf16_f32 v183, v119, v151
	global_store_dwordx4 v216, v[180:183], s[28:29] nt
	v_lshlrev_b32_e32 v249, 16, v184
	v_and_b32_e32 v250, s79, v184
	v_mul_f32_e32 v120, v120, v247
	v_mul_f32_e32 v152, v152, v247
	v_mul_f32_e32 v120, v120, v192
	v_mul_f32_e32 v152, v152, v193
	v_mul_f32_e32 v120, v120, v249
	v_mul_f32_e32 v152, v152, v250
	v_cvt_pk_bf16_f32 v184, v120, v152
	v_lshlrev_b32_e32 v251, 16, v185
	v_and_b32_e32 v252, s79, v185
	v_mul_f32_e32 v121, v121, v247
	v_mul_f32_e32 v153, v153, v247
	v_mul_f32_e32 v121, v121, v194
	v_mul_f32_e32 v153, v153, v195
	v_mul_f32_e32 v121, v121, v251
	v_mul_f32_e32 v153, v153, v252
	v_cvt_pk_bf16_f32 v185, v121, v153
	v_lshlrev_b32_e32 v249, 16, v186
	v_and_b32_e32 v250, s79, v186
	v_mul_f32_e32 v122, v122, v247
	v_mul_f32_e32 v154, v154, v247
	v_mul_f32_e32 v122, v122, v196
	v_mul_f32_e32 v154, v154, v197
	v_mul_f32_e32 v122, v122, v249
	v_mul_f32_e32 v154, v154, v250
	v_cvt_pk_bf16_f32 v186, v122, v154
	v_lshlrev_b32_e32 v251, 16, v187
	v_and_b32_e32 v252, s79, v187
	v_mul_f32_e32 v123, v123, v247
	v_mul_f32_e32 v155, v155, v247
	v_mul_f32_e32 v123, v123, v198
; #define GASP __attribute__((address_space(1)))
; __device__ __forceinline__ unsigned pk2(float lo, float hi) { return f2bf(lo) | (f2bf(hi) << 16); }
; __device__ __forceinline__ float bflo(unsigned w) { return __uint_as_float(w << 16); }
; __device__ __forceinline__ float bfhi(unsigned w) { return __uint_as_float(w & 0xffff0000u); }
; __global__ void __launch_bounds__(NWAVES * 64, 2) fwd_kernel(Args args) {
;     ...
;                         for (int it = 0; it < 8; ++it) { const size_t off = (r0 + it * 4) * 1024 + h * 128 + c8;
;                             pp[it] = *(const GASP v4u*)(O1 + off); qq[it] = *(const GASP v4u*)(O2 + off);
;                             zz[it] = *(const GASP v4u*)(ZA + off); }
; #pragma unroll
;                         for (int it = 0; it < 8; ++it) { const size_t row = r0 + it * 4; const v4u p = pp[it], q = qq[it], z = zz[it];
;                             float d[8]; float ss = 0.f;
; #pragma unroll
;                             for (int e = 0; e < 4; ++e) { d[2 * e] = bflo(p[e]) - lam * bflo(q[e]); d[2 * e + 1] = bfhi(p[e]) - lam * bfhi(q[e]); ss += d[2 * e] * d[2 * e] + d[2 * e + 1] * d[2 * e + 1]; }
;     ...
;                             o[0] = pk2(d[0] * r * sg0[0] * bflo(z[0]), d[1] * r * sg0[1] * bfhi(z[0])); o[1] = pk2(d[2] * r * sg0[2] * bflo(z[1]), d[3] * r * sg0[3] * bfhi(z[1]));
;                             o[2] = pk2(d[4] * r * sg1[0] * bflo(z[2]), d[5] * r * sg1[1] * bfhi(z[2])); o[3] = pk2(d[6] * r * sg1[2] * bflo(z[3]), d[7] * r * sg1[3] * bfhi(z[3]));
;                             *(GASP v4u*)(YCAT + row * 2048 + 1024 + h * 128 + c8) = o; }
	v_mul_f32_e32 v155, v155, v199
	v_mul_f32_e32 v123, v123, v251
	v_mul_f32_e32 v155, v155, v252
	v_cvt_pk_bf16_f32 v187, v123, v155
	global_store_dwordx4 v217, v[184:187], s[28:29] nt
	v_lshlrev_b32_e32 v249, 16, v188
	v_and_b32_e32 v250, s79, v188
	v_mul_f32_e32 v124, v124, v248
	v_mul_f32_e32 v156, v156, v248
	v_mul_f32_e32 v124, v124, v192
	v_mul_f32_e32 v156, v156, v193
	v_mul_f32_e32 v124, v124, v249
	v_mul_f32_e32 v156, v156, v250
	v_cvt_pk_bf16_f32 v188, v124, v156
	v_lshlrev_b32_e32 v251, 16, v189
	v_and_b32_e32 v252, s79, v189
	v_mul_f32_e32 v125, v125, v248
	v_mul_f32_e32 v157, v157, v248
	v_mul_f32_e32 v125, v125, v194
	v_mul_f32_e32 v157, v157, v195
	v_mul_f32_e32 v125, v125, v251
	v_mul_f32_e32 v157, v157, v252
	v_cvt_pk_bf16_f32 v189, v125, v157
	v_lshlrev_b32_e32 v249, 16, v190
	v_and_b32_e32 v250, s79, v190
	v_mul_f32_e32 v126, v126, v248
	v_mul_f32_e32 v158, v158, v248
	v_mul_f32_e32 v126, v126, v196
	v_mul_f32_e32 v158, v158, v197
	v_mul_f32_e32 v126, v126, v249
	v_mul_f32_e32 v158, v158, v250
	v_cvt_pk_bf16_f32 v190, v126, v158
	v_lshlrev_b32_e32 v251, 16, v191
	v_and_b32_e32 v252, s79, v191
	v_mul_f32_e32 v127, v127, v248
	v_mul_f32_e32 v159, v159, v248
	v_mul_f32_e32 v127, v127, v198
	v_mul_f32_e32 v159, v159, v199
	v_mul_f32_e32 v127, v127, v251
	v_mul_f32_e32 v159, v159, v252
	v_cvt_pk_bf16_f32 v191, v127, v159
	global_store_dwordx4 v219, v[188:191], s[28:29] nt
	s_lshl_b32 s21, s75, 23
	s_lshl_b32 s32, s57, 19
	s_add_u32 s21, s21, s32
	s_lshl_b32 s32, s61, 1
	s_add_u32 s21, s21, s32
	s_add_u32 s21, s21, 0xda00000
	s_add_u32 s0, s8, s21
	s_addc_u32 s1, s9, 0
	s_add_u32 s4, s0, 0x4000000
	s_addc_u32 s5, s1, 0
	s_add_u32 s6, s0, 0x24000000
	s_addc_u32 s7, s1, 0
	global_load_dwordx4 v[96:99], v200, s[0:1] nt
	global_load_dwordx4 v[128:131], v200, s[4:5] nt
	global_load_dwordx4 v[100:103], v201, s[0:1] nt
	global_load_dwordx4 v[132:135], v201, s[4:5] nt
	global_load_dwordx4 v[104:107], v202, s[0:1] nt
	global_load_dwordx4 v[136:139], v202, s[4:5] nt
	global_load_dwordx4 v[108:111], v203, s[0:1] nt
	global_load_dwordx4 v[140:143], v203, s[4:5] nt
	global_load_dwordx4 v[112:115], v204, s[0:1] nt
	global_load_dwordx4 v[144:147], v204, s[4:5] nt
	global_load_dwordx4 v[116:119], v206, s[0:1] nt
	global_load_dwordx4 v[148:151], v206, s[4:5] nt
	global_load_dwordx4 v[120:123], v207, s[0:1] nt
	global_load_dwordx4 v[152:155], v207, s[4:5] nt
	global_load_dwordx4 v[124:127], v208, s[0:1] nt
	global_load_dwordx4 v[156:159], v208, s[4:5] nt
	global_load_dwordx4 v[160:163], v200, s[6:7] nt
	global_load_dwordx4 v[164:167], v201, s[6:7] nt
	global_load_dwordx4 v[168:171], v202, s[6:7] nt
	global_load_dwordx4 v[172:175], v203, s[6:7] nt
	global_load_dwordx4 v[176:179], v204, s[6:7] nt
	global_load_dwordx4 v[180:183], v206, s[6:7] nt
	global_load_dwordx4 v[184:187], v207, s[6:7] nt
	global_load_dwordx4 v[188:191], v208, s[6:7] nt
	s_lshl_b32 s21, s75, 24
	s_lshl_b32 s32, s60, 20
	s_add_u32 s21, s21, s32
	s_lshl_b32 s32, s61, 1
	s_add_u32 s21, s21, s32
	s_add_u32 s21, s21, 0x15a00800
	s_add_u32 s28, s8, s21
	s_addc_u32 s29, s9, 0
	s_waitcnt vmcnt(32)
	v_lshlrev_b32_e32 v249, 16, v32
	v_and_b32_e32 v250, s79, v32
	v_lshlrev_b32_e32 v251, 16, v0
	v_and_b32_e32 v252, s79, v0
	v_fma_f32 v0, -s26, v249, v251
	v_fma_f32 v32, -s26, v250, v252
	v_lshlrev_b32_e32 v249, 16, v33
	v_and_b32_e32 v250, s79, v33
	v_lshlrev_b32_e32 v251, 16, v1
	v_and_b32_e32 v252, s79, v1
	v_mul_f32_e32 v241, v0, v0
	v_mul_f32_e32 v222, v32, v32
	v_fma_f32 v1, -s26, v249, v251
	v_fma_f32 v33, -s26, v250, v252
	v_lshlrev_b32_e32 v249, 16, v34
	v_and_b32_e32 v250, s79, v34
	v_lshlrev_b32_e32 v251, 16, v2
	v_and_b32_e32 v252, s79, v2
	v_fmac_f32_e32 v241, v1, v1
	v_fmac_f32_e32 v222, v33, v33
	v_fma_f32 v2, -s26, v249, v251
	v_fma_f32 v34, -s26, v250, v252
	v_lshlrev_b32_e32 v249, 16, v35
	v_and_b32_e32 v250, s79, v35
	v_lshlrev_b32_e32 v251, 16, v3
	v_and_b32_e32 v252, s79, v3
	v_fmac_f32_e32 v241, v2, v2
	v_fmac_f32_e32 v222, v34, v34
	v_fma_f32 v3, -s26, v249, v251
	v_fma_f32 v35, -s26, v250, v252
	s_nop 0
	v_fmac_f32_e32 v241, v3, v3
	v_fmac_f32_e32 v222, v35, v35
	v_lshlrev_b32_e32 v249, 16, v36
	v_and_b32_e32 v250, s79, v36
	v_lshlrev_b32_e32 v251, 16, v4
	v_and_b32_e32 v252, s79, v4
	v_fma_f32 v4, -s26, v249, v251
	v_fma_f32 v36, -s26, v250, v252
	v_lshlrev_b32_e32 v249, 16, v37
	v_and_b32_e32 v250, s79, v37
	v_lshlrev_b32_e32 v251, 16, v5
	v_and_b32_e32 v252, s79, v5
	v_mul_f32_e32 v242, v4, v4
	v_mul_f32_e32 v223, v36, v36
	v_fma_f32 v5, -s26, v249, v251
	v_fma_f32 v37, -s26, v250, v252
	v_lshlrev_b32_e32 v249, 16, v38
	v_and_b32_e32 v250, s79, v38
	v_lshlrev_b32_e32 v251, 16, v6
	v_and_b32_e32 v252, s79, v6
	v_fmac_f32_e32 v242, v5, v5
	v_fmac_f32_e32 v223, v37, v37
	v_fma_f32 v6, -s26, v249, v251
	v_fma_f32 v38, -s26, v250, v252
	v_lshlrev_b32_e32 v249, 16, v39
	v_and_b32_e32 v250, s79, v39
	v_lshlrev_b32_e32 v251, 16, v7
	v_and_b32_e32 v252, s79, v7
	v_fmac_f32_e32 v242, v6, v6
	v_fmac_f32_e32 v223, v38, v38
	v_fma_f32 v7, -s26, v249, v251
	v_fma_f32 v39, -s26, v250, v252
	s_nop 0
	v_fmac_f32_e32 v242, v7, v7
	v_fmac_f32_e32 v223, v39, v39
	v_lshlrev_b32_e32 v249, 16, v40
	v_and_b32_e32 v250, s79, v40
	v_lshlrev_b32_e32 v251, 16, v8
	v_and_b32_e32 v252, s79, v8
	v_fma_f32 v8, -s26, v249, v251
	v_fma_f32 v40, -s26, v250, v252
	v_lshlrev_b32_e32 v249, 16, v41
	v_and_b32_e32 v250, s79, v41
	v_lshlrev_b32_e32 v251, 16, v9
	v_and_b32_e32 v252, s79, v9
	v_mul_f32_e32 v243, v8, v8
	v_mul_f32_e32 v224, v40, v40
	v_fma_f32 v9, -s26, v249, v251
	v_fma_f32 v41, -s26, v250, v252
	v_lshlrev_b32_e32 v249, 16, v42
	v_and_b32_e32 v250, s79, v42
	v_lshlrev_b32_e32 v251, 16, v10
; __device__ __forceinline__ float bflo(unsigned w) { return __uint_as_float(w << 16); }
; __device__ __forceinline__ float bfhi(unsigned w) { return __uint_as_float(w & 0xffff0000u); }
; __global__ void __launch_bounds__(NWAVES * 64, 2) fwd_kernel(Args args) {
;     ...
;                         for (int it = 0; it < 8; ++it) { const size_t row = r0 + it * 4; const v4u p = pp[it], q = qq[it], z = zz[it];
;                             float d[8]; float ss = 0.f;
; #pragma unroll
;                             for (int e = 0; e < 4; ++e) { d[2 * e] = bflo(p[e]) - lam * bflo(q[e]); d[2 * e + 1] = bfhi(p[e]) - lam * bfhi(q[e]); ss += d[2 * e] * d[2 * e] + d[2 * e + 1] * d[2 * e + 1]; }
	v_and_b32_e32 v252, s79, v10
	v_fmac_f32_e32 v243, v9, v9
	v_fmac_f32_e32 v224, v41, v41
	v_fma_f32 v10, -s26, v249, v251
	v_fma_f32 v42, -s26, v250, v252
	v_lshlrev_b32_e32 v249, 16, v43
	v_and_b32_e32 v250, s79, v43
	v_lshlrev_b32_e32 v251, 16, v11
	v_and_b32_e32 v252, s79, v11
	v_fmac_f32_e32 v243, v10, v10
	v_fmac_f32_e32 v224, v42, v42
	v_fma_f32 v11, -s26, v249, v251
	v_fma_f32 v43, -s26, v250, v252
	s_nop 0
	v_fmac_f32_e32 v243, v11, v11
	v_fmac_f32_e32 v224, v43, v43
	v_lshlrev_b32_e32 v249, 16, v44
	v_and_b32_e32 v250, s79, v44
	v_lshlrev_b32_e32 v251, 16, v12
	v_and_b32_e32 v252, s79, v12
	v_fma_f32 v12, -s26, v249, v251
	v_fma_f32 v44, -s26, v250, v252
	v_lshlrev_b32_e32 v249, 16, v45
	v_and_b32_e32 v250, s79, v45
	v_lshlrev_b32_e32 v251, 16, v13
	v_and_b32_e32 v252, s79, v13
	v_mul_f32_e32 v244, v12, v12
	v_mul_f32_e32 v225, v44, v44
	v_fma_f32 v13, -s26, v249, v251
	v_fma_f32 v45, -s26, v250, v252
	v_lshlrev_b32_e32 v249, 16, v46
	v_and_b32_e32 v250, s79, v46
	v_lshlrev_b32_e32 v251, 16, v14
	v_and_b32_e32 v252, s79, v14
	v_fmac_f32_e32 v244, v13, v13
	v_fmac_f32_e32 v225, v45, v45
	v_fma_f32 v14, -s26, v249, v251
	v_fma_f32 v46, -s26, v250, v252
	v_lshlrev_b32_e32 v249, 16, v47
	v_and_b32_e32 v250, s79, v47
	v_lshlrev_b32_e32 v251, 16, v15
	v_and_b32_e32 v252, s79, v15
	v_fmac_f32_e32 v244, v14, v14
	v_fmac_f32_e32 v225, v46, v46
	v_fma_f32 v15, -s26, v249, v251
	v_fma_f32 v47, -s26, v250, v252
	s_nop 0
	v_fmac_f32_e32 v244, v15, v15
	v_fmac_f32_e32 v225, v47, v47
	v_lshlrev_b32_e32 v249, 16, v48
	v_and_b32_e32 v250, s79, v48
	v_lshlrev_b32_e32 v251, 16, v16
	v_and_b32_e32 v252, s79, v16
	v_fma_f32 v16, -s26, v249, v251
	v_fma_f32 v48, -s26, v250, v252
	v_lshlrev_b32_e32 v249, 16, v49
	v_and_b32_e32 v250, s79, v49
	v_lshlrev_b32_e32 v251, 16, v17
	v_and_b32_e32 v252, s79, v17
	v_mul_f32_e32 v245, v16, v16
	v_mul_f32_e32 v226, v48, v48
	v_fma_f32 v17, -s26, v249, v251
	v_fma_f32 v49, -s26, v250, v252
	v_lshlrev_b32_e32 v249, 16, v50
	v_and_b32_e32 v250, s79, v50
	v_lshlrev_b32_e32 v251, 16, v18
	v_and_b32_e32 v252, s79, v18
	v_fmac_f32_e32 v245, v17, v17
	v_fmac_f32_e32 v226, v49, v49
	v_fma_f32 v18, -s26, v249, v251
	v_fma_f32 v50, -s26, v250, v252
	v_lshlrev_b32_e32 v249, 16, v51
	v_and_b32_e32 v250, s79, v51
	v_lshlrev_b32_e32 v251, 16, v19
	v_and_b32_e32 v252, s79, v19
	v_fmac_f32_e32 v245, v18, v18
	v_fmac_f32_e32 v226, v50, v50
	v_fma_f32 v19, -s26, v249, v251
	v_fma_f32 v51, -s26, v250, v252
	s_nop 0
	v_fmac_f32_e32 v245, v19, v19
	v_fmac_f32_e32 v226, v51, v51
	v_lshlrev_b32_e32 v249, 16, v52
	v_and_b32_e32 v250, s79, v52
	v_lshlrev_b32_e32 v251, 16, v20
	v_and_b32_e32 v252, s79, v20
	v_fma_f32 v20, -s26, v249, v251
	v_fma_f32 v52, -s26, v250, v252
	v_lshlrev_b32_e32 v249, 16, v53
	v_and_b32_e32 v250, s79, v53
	v_lshlrev_b32_e32 v251, 16, v21
	v_and_b32_e32 v252, s79, v21
	v_mul_f32_e32 v246, v20, v20
	v_mul_f32_e32 v227, v52, v52
	v_fma_f32 v21, -s26, v249, v251
	v_fma_f32 v53, -s26, v250, v252
	v_lshlrev_b32_e32 v249, 16, v54
	v_and_b32_e32 v250, s79, v54
	v_lshlrev_b32_e32 v251, 16, v22
	v_and_b32_e32 v252, s79, v22
	v_fmac_f32_e32 v246, v21, v21
	v_fmac_f32_e32 v227, v53, v53
	v_fma_f32 v22, -s26, v249, v251
	v_fma_f32 v54, -s26, v250, v252
	v_lshlrev_b32_e32 v249, 16, v55
	v_and_b32_e32 v250, s79, v55
	v_lshlrev_b32_e32 v251, 16, v23
	v_and_b32_e32 v252, s79, v23
	v_fmac_f32_e32 v246, v22, v22
	v_fmac_f32_e32 v227, v54, v54
	v_fma_f32 v23, -s26, v249, v251
	v_fma_f32 v55, -s26, v250, v252
	s_nop 0
	v_fmac_f32_e32 v246, v23, v23
	v_fmac_f32_e32 v227, v55, v55
	v_lshlrev_b32_e32 v249, 16, v56
	v_and_b32_e32 v250, s79, v56
	v_lshlrev_b32_e32 v251, 16, v24
	v_and_b32_e32 v252, s79, v24
	v_fma_f32 v24, -s26, v249, v251
	v_fma_f32 v56, -s26, v250, v252
	v_lshlrev_b32_e32 v249, 16, v57
	v_and_b32_e32 v250, s79, v57
	v_lshlrev_b32_e32 v251, 16, v25
	v_and_b32_e32 v252, s79, v25
	v_mul_f32_e32 v247, v24, v24
	v_mul_f32_e32 v228, v56, v56
	v_fma_f32 v25, -s26, v249, v251
	v_fma_f32 v57, -s26, v250, v252
	v_lshlrev_b32_e32 v249, 16, v58
	v_and_b32_e32 v250, s79, v58
	v_lshlrev_b32_e32 v251, 16, v26
	v_and_b32_e32 v252, s79, v26
	v_fmac_f32_e32 v247, v25, v25
	v_fmac_f32_e32 v228, v57, v57
	v_fma_f32 v26, -s26, v249, v251
	v_fma_f32 v58, -s26, v250, v252
	v_lshlrev_b32_e32 v249, 16, v59
	v_and_b32_e32 v250, s79, v59
	v_lshlrev_b32_e32 v251, 16, v27
	v_and_b32_e32 v252, s79, v27
	v_fmac_f32_e32 v247, v26, v26
	v_fmac_f32_e32 v228, v58, v58
	v_fma_f32 v27, -s26, v249, v251
	v_fma_f32 v59, -s26, v250, v252
	s_nop 0
	v_fmac_f32_e32 v247, v27, v27
	v_fmac_f32_e32 v228, v59, v59
	v_lshlrev_b32_e32 v249, 16, v60
	v_and_b32_e32 v250, s79, v60
	v_lshlrev_b32_e32 v251, 16, v28
	v_and_b32_e32 v252, s79, v28
	v_fma_f32 v28, -s26, v249, v251
	v_fma_f32 v60, -s26, v250, v252
	v_lshlrev_b32_e32 v249, 16, v61
	v_and_b32_e32 v250, s79, v61
	v_lshlrev_b32_e32 v251, 16, v29
	v_and_b32_e32 v252, s79, v29
	v_mul_f32_e32 v248, v28, v28
	v_mul_f32_e32 v229, v60, v60
	v_fma_f32 v29, -s26, v249, v251
	v_fma_f32 v61, -s26, v250, v252
	v_lshlrev_b32_e32 v249, 16, v62
	v_and_b32_e32 v250, s79, v62
	v_lshlrev_b32_e32 v251, 16, v30
	v_and_b32_e32 v252, s79, v30
	v_fmac_f32_e32 v248, v29, v29
	v_fmac_f32_e32 v229, v61, v61
	v_fma_f32 v30, -s26, v249, v251
	v_fma_f32 v62, -s26, v250, v252
	v_lshlrev_b32_e32 v249, 16, v63
	v_and_b32_e32 v250, s79, v63
	v_lshlrev_b32_e32 v251, 16, v31
	v_and_b32_e32 v252, s79, v31
	v_fmac_f32_e32 v248, v30, v30
	v_fmac_f32_e32 v229, v62, v62
	v_fma_f32 v31, -s26, v249, v251
	v_fma_f32 v63, -s26, v250, v252
	s_nop 0
	v_fmac_f32_e32 v248, v31, v31
	v_fmac_f32_e32 v229, v63, v63
	v_add_f32_e32 v241, v241, v222
; #define GASP __attribute__((address_space(1)))
; __device__ __forceinline__ float lane_xor(float v, int lane, int o) { return __int_as_float(__builtin_amdgcn_ds_bpermute((lane ^ o) << 2, __float_as_int(v))); }
; __device__ __forceinline__ unsigned pk2(float lo, float hi) { return f2bf(lo) | (f2bf(hi) << 16); }
; __device__ __forceinline__ float bflo(unsigned w) { return __uint_as_float(w << 16); }
; __device__ __forceinline__ float bfhi(unsigned w) { return __uint_as_float(w & 0xffff0000u); }
; __global__ void __launch_bounds__(NWAVES * 64, 2) fwd_kernel(Args args) {
;     ...
;                             for (int e = 0; e < 4; ++e) { d[2 * e] = bflo(p[e]) - lam * bflo(q[e]); d[2 * e + 1] = bfhi(p[e]) - lam * bfhi(q[e]); ss += d[2 * e] * d[2 * e] + d[2 * e + 1] * d[2 * e + 1]; }
;                             ss += lane_xor(ss, ln, 1); ss += lane_xor(ss, ln, 2); ss += lane_xor(ss, ln, 4); ss += lane_xor(ss, ln, 8);
;                             const float r = 1.0f / sqrtf(ss * (1.f / 128.f) + 1e-6f);
;                             v4u o;
;                             o[0] = pk2(d[0] * r * sg0[0] * bflo(z[0]), d[1] * r * sg0[1] * bfhi(z[0])); o[1] = pk2(d[2] * r * sg0[2] * bflo(z[1]), d[3] * r * sg0[3] * bfhi(z[1]));
;                             o[2] = pk2(d[4] * r * sg1[0] * bflo(z[2]), d[5] * r * sg1[1] * bfhi(z[2])); o[3] = pk2(d[6] * r * sg1[2] * bflo(z[3]), d[7] * r * sg1[3] * bfhi(z[3]));
;                             *(GASP v4u*)(YCAT + row * 2048 + 1024 + h * 128 + c8) = o; }
	v_add_f32_e32 v242, v242, v223
	v_add_f32_e32 v243, v243, v224
	v_add_f32_e32 v244, v244, v225
	v_add_f32_e32 v245, v245, v226
	v_add_f32_e32 v246, v246, v227
	v_add_f32_e32 v247, v247, v228
	v_add_f32_e32 v248, v248, v229
	v_add_f32_dpp v241, v241, v241 quad_perm:[1,0,3,2] row_mask:0xf bank_mask:0xf
	v_add_f32_dpp v242, v242, v242 quad_perm:[1,0,3,2] row_mask:0xf bank_mask:0xf
	v_add_f32_dpp v243, v243, v243 quad_perm:[1,0,3,2] row_mask:0xf bank_mask:0xf
	v_add_f32_dpp v244, v244, v244 quad_perm:[1,0,3,2] row_mask:0xf bank_mask:0xf
	v_add_f32_dpp v245, v245, v245 quad_perm:[1,0,3,2] row_mask:0xf bank_mask:0xf
	v_add_f32_dpp v246, v246, v246 quad_perm:[1,0,3,2] row_mask:0xf bank_mask:0xf
	v_add_f32_dpp v247, v247, v247 quad_perm:[1,0,3,2] row_mask:0xf bank_mask:0xf
	v_add_f32_dpp v248, v248, v248 quad_perm:[1,0,3,2] row_mask:0xf bank_mask:0xf
	v_add_f32_dpp v241, v241, v241 quad_perm:[2,3,0,1] row_mask:0xf bank_mask:0xf
	v_add_f32_dpp v242, v242, v242 quad_perm:[2,3,0,1] row_mask:0xf bank_mask:0xf
	v_add_f32_dpp v243, v243, v243 quad_perm:[2,3,0,1] row_mask:0xf bank_mask:0xf
	v_add_f32_dpp v244, v244, v244 quad_perm:[2,3,0,1] row_mask:0xf bank_mask:0xf
	v_add_f32_dpp v245, v245, v245 quad_perm:[2,3,0,1] row_mask:0xf bank_mask:0xf
	v_add_f32_dpp v246, v246, v246 quad_perm:[2,3,0,1] row_mask:0xf bank_mask:0xf
	v_add_f32_dpp v247, v247, v247 quad_perm:[2,3,0,1] row_mask:0xf bank_mask:0xf
	v_add_f32_dpp v248, v248, v248 quad_perm:[2,3,0,1] row_mask:0xf bank_mask:0xf
	v_add_f32_dpp v241, v241, v241 row_ror:4 row_mask:0xf bank_mask:0xf
	v_add_f32_dpp v242, v242, v242 row_ror:4 row_mask:0xf bank_mask:0xf
	v_add_f32_dpp v243, v243, v243 row_ror:4 row_mask:0xf bank_mask:0xf
	v_add_f32_dpp v244, v244, v244 row_ror:4 row_mask:0xf bank_mask:0xf
	v_add_f32_dpp v245, v245, v245 row_ror:4 row_mask:0xf bank_mask:0xf
	v_add_f32_dpp v246, v246, v246 row_ror:4 row_mask:0xf bank_mask:0xf
	v_add_f32_dpp v247, v247, v247 row_ror:4 row_mask:0xf bank_mask:0xf
	v_add_f32_dpp v248, v248, v248 row_ror:4 row_mask:0xf bank_mask:0xf
	v_add_f32_dpp v241, v241, v241 row_ror:8 row_mask:0xf bank_mask:0xf
	v_add_f32_dpp v242, v242, v242 row_ror:8 row_mask:0xf bank_mask:0xf
	v_add_f32_dpp v243, v243, v243 row_ror:8 row_mask:0xf bank_mask:0xf
	v_add_f32_dpp v244, v244, v244 row_ror:8 row_mask:0xf bank_mask:0xf
	v_add_f32_dpp v245, v245, v245 row_ror:8 row_mask:0xf bank_mask:0xf
	v_add_f32_dpp v246, v246, v246 row_ror:8 row_mask:0xf bank_mask:0xf
	v_add_f32_dpp v247, v247, v247 row_ror:8 row_mask:0xf bank_mask:0xf
	v_add_f32_dpp v248, v248, v248 row_ror:8 row_mask:0xf bank_mask:0xf
	v_fmamk_f32 v241, v241, 0x3c000000, v231
	v_fmamk_f32 v242, v242, 0x3c000000, v231
	v_fmamk_f32 v243, v243, 0x3c000000, v231
	v_fmamk_f32 v244, v244, 0x3c000000, v231
	v_fmamk_f32 v245, v245, 0x3c000000, v231
	v_fmamk_f32 v246, v246, 0x3c000000, v231
	v_fmamk_f32 v247, v247, 0x3c000000, v231
	v_fmamk_f32 v248, v248, 0x3c000000, v231
	v_rsq_f32_e32 v241, v241
	v_rsq_f32_e32 v242, v242
	v_rsq_f32_e32 v243, v243
	v_rsq_f32_e32 v244, v244
	v_rsq_f32_e32 v245, v245
	v_rsq_f32_e32 v246, v246
	v_rsq_f32_e32 v247, v247
	v_rsq_f32_e32 v248, v248
	v_lshlrev_b32_e32 v249, 16, v64
	v_and_b32_e32 v250, s79, v64
	v_mul_f32_e32 v0, v0, v241
	v_mul_f32_e32 v32, v32, v241
	v_mul_f32_e32 v0, v0, v192
	v_mul_f32_e32 v32, v32, v193
	v_mul_f32_e32 v0, v0, v249
	v_mul_f32_e32 v32, v32, v250
	v_cvt_pk_bf16_f32 v64, v0, v32
	v_lshlrev_b32_e32 v251, 16, v65
	v_and_b32_e32 v252, s79, v65
	v_mul_f32_e32 v1, v1, v241
	v_mul_f32_e32 v33, v33, v241
	v_mul_f32_e32 v1, v1, v194
	v_mul_f32_e32 v33, v33, v195
	v_mul_f32_e32 v1, v1, v251
	v_mul_f32_e32 v33, v33, v252
	v_cvt_pk_bf16_f32 v65, v1, v33
	v_lshlrev_b32_e32 v249, 16, v66
	v_and_b32_e32 v250, s79, v66
	v_mul_f32_e32 v2, v2, v241
	v_mul_f32_e32 v34, v34, v241
	v_mul_f32_e32 v2, v2, v196
	v_mul_f32_e32 v34, v34, v197
	v_mul_f32_e32 v2, v2, v249
	v_mul_f32_e32 v34, v34, v250
	v_cvt_pk_bf16_f32 v66, v2, v34
	v_lshlrev_b32_e32 v251, 16, v67
	v_and_b32_e32 v252, s79, v67
	v_mul_f32_e32 v3, v3, v241
	v_mul_f32_e32 v35, v35, v241
	v_mul_f32_e32 v3, v3, v198
	v_mul_f32_e32 v35, v35, v199
	v_mul_f32_e32 v3, v3, v251
	v_mul_f32_e32 v35, v35, v252
	v_cvt_pk_bf16_f32 v67, v3, v35
	global_store_dwordx4 v209, v[64:67], s[28:29] nt
	v_lshlrev_b32_e32 v249, 16, v68
	v_and_b32_e32 v250, s79, v68
	v_mul_f32_e32 v4, v4, v242
	v_mul_f32_e32 v36, v36, v242
	v_mul_f32_e32 v4, v4, v192
	v_mul_f32_e32 v36, v36, v193
	v_mul_f32_e32 v4, v4, v249
	v_mul_f32_e32 v36, v36, v250
	v_cvt_pk_bf16_f32 v68, v4, v36
	v_lshlrev_b32_e32 v251, 16, v69
	v_and_b32_e32 v252, s79, v69
	v_mul_f32_e32 v5, v5, v242
	v_mul_f32_e32 v37, v37, v242
	v_mul_f32_e32 v5, v5, v194
	v_mul_f32_e32 v37, v37, v195
	v_mul_f32_e32 v5, v5, v251
	v_mul_f32_e32 v37, v37, v252
	v_cvt_pk_bf16_f32 v69, v5, v37
	v_lshlrev_b32_e32 v249, 16, v70
	v_and_b32_e32 v250, s79, v70
	v_mul_f32_e32 v6, v6, v242
	v_mul_f32_e32 v38, v38, v242
	v_mul_f32_e32 v6, v6, v196
	v_mul_f32_e32 v38, v38, v197
	v_mul_f32_e32 v6, v6, v249
	v_mul_f32_e32 v38, v38, v250
	v_cvt_pk_bf16_f32 v70, v6, v38
	v_lshlrev_b32_e32 v251, 16, v71
	v_and_b32_e32 v252, s79, v71
	v_mul_f32_e32 v7, v7, v242
	v_mul_f32_e32 v39, v39, v242
	v_mul_f32_e32 v7, v7, v198
	v_mul_f32_e32 v39, v39, v199
	v_mul_f32_e32 v7, v7, v251
	v_mul_f32_e32 v39, v39, v252
	v_cvt_pk_bf16_f32 v71, v7, v39
	global_store_dwordx4 v210, v[68:71], s[28:29] nt
	v_lshlrev_b32_e32 v249, 16, v72
	v_and_b32_e32 v250, s79, v72
	v_mul_f32_e32 v8, v8, v243
	v_mul_f32_e32 v40, v40, v243
	v_mul_f32_e32 v8, v8, v192
	v_mul_f32_e32 v40, v40, v193
	v_mul_f32_e32 v8, v8, v249
	v_mul_f32_e32 v40, v40, v250
; #define GASP __attribute__((address_space(1)))
; __device__ __forceinline__ unsigned pk2(float lo, float hi) { return f2bf(lo) | (f2bf(hi) << 16); }
; __device__ __forceinline__ float bflo(unsigned w) { return __uint_as_float(w << 16); }
; __device__ __forceinline__ float bfhi(unsigned w) { return __uint_as_float(w & 0xffff0000u); }
; __global__ void __launch_bounds__(NWAVES * 64, 2) fwd_kernel(Args args) {
;     ...
;                             o[0] = pk2(d[0] * r * sg0[0] * bflo(z[0]), d[1] * r * sg0[1] * bfhi(z[0])); o[1] = pk2(d[2] * r * sg0[2] * bflo(z[1]), d[3] * r * sg0[3] * bfhi(z[1]));
;                             o[2] = pk2(d[4] * r * sg1[0] * bflo(z[2]), d[5] * r * sg1[1] * bfhi(z[2])); o[3] = pk2(d[6] * r * sg1[2] * bflo(z[3]), d[7] * r * sg1[3] * bfhi(z[3]));
;                             *(GASP v4u*)(YCAT + row * 2048 + 1024 + h * 128 + c8) = o; }
	v_cvt_pk_bf16_f32 v72, v8, v40
	v_lshlrev_b32_e32 v251, 16, v73
	v_and_b32_e32 v252, s79, v73
	v_mul_f32_e32 v9, v9, v243
	v_mul_f32_e32 v41, v41, v243
	v_mul_f32_e32 v9, v9, v194
	v_mul_f32_e32 v41, v41, v195
	v_mul_f32_e32 v9, v9, v251
	v_mul_f32_e32 v41, v41, v252
	v_cvt_pk_bf16_f32 v73, v9, v41
	v_lshlrev_b32_e32 v249, 16, v74
	v_and_b32_e32 v250, s79, v74
	v_mul_f32_e32 v10, v10, v243
	v_mul_f32_e32 v42, v42, v243
	v_mul_f32_e32 v10, v10, v196
	v_mul_f32_e32 v42, v42, v197
	v_mul_f32_e32 v10, v10, v249
	v_mul_f32_e32 v42, v42, v250
	v_cvt_pk_bf16_f32 v74, v10, v42
	v_lshlrev_b32_e32 v251, 16, v75
	v_and_b32_e32 v252, s79, v75
	v_mul_f32_e32 v11, v11, v243
	v_mul_f32_e32 v43, v43, v243
	v_mul_f32_e32 v11, v11, v198
	v_mul_f32_e32 v43, v43, v199
	v_mul_f32_e32 v11, v11, v251
	v_mul_f32_e32 v43, v43, v252
	v_cvt_pk_bf16_f32 v75, v11, v43
	global_store_dwordx4 v211, v[72:75], s[28:29] nt
	v_lshlrev_b32_e32 v249, 16, v76
	v_and_b32_e32 v250, s79, v76
	v_mul_f32_e32 v12, v12, v244
	v_mul_f32_e32 v44, v44, v244
	v_mul_f32_e32 v12, v12, v192
	v_mul_f32_e32 v44, v44, v193
	v_mul_f32_e32 v12, v12, v249
	v_mul_f32_e32 v44, v44, v250
	v_cvt_pk_bf16_f32 v76, v12, v44
	v_lshlrev_b32_e32 v251, 16, v77
	v_and_b32_e32 v252, s79, v77
	v_mul_f32_e32 v13, v13, v244
	v_mul_f32_e32 v45, v45, v244
	v_mul_f32_e32 v13, v13, v194
	v_mul_f32_e32 v45, v45, v195
	v_mul_f32_e32 v13, v13, v251
	v_mul_f32_e32 v45, v45, v252
	v_cvt_pk_bf16_f32 v77, v13, v45
	v_lshlrev_b32_e32 v249, 16, v78
	v_and_b32_e32 v250, s79, v78
	v_mul_f32_e32 v14, v14, v244
	v_mul_f32_e32 v46, v46, v244
	v_mul_f32_e32 v14, v14, v196
	v_mul_f32_e32 v46, v46, v197
	v_mul_f32_e32 v14, v14, v249
	v_mul_f32_e32 v46, v46, v250
	v_cvt_pk_bf16_f32 v78, v14, v46
	v_lshlrev_b32_e32 v251, 16, v79
	v_and_b32_e32 v252, s79, v79
	v_mul_f32_e32 v15, v15, v244
	v_mul_f32_e32 v47, v47, v244
	v_mul_f32_e32 v15, v15, v198
	v_mul_f32_e32 v47, v47, v199
	v_mul_f32_e32 v15, v15, v251
	v_mul_f32_e32 v47, v47, v252
	v_cvt_pk_bf16_f32 v79, v15, v47
	global_store_dwordx4 v214, v[76:79], s[28:29] nt
	v_lshlrev_b32_e32 v249, 16, v80
	v_and_b32_e32 v250, s79, v80
	v_mul_f32_e32 v16, v16, v245
	v_mul_f32_e32 v48, v48, v245
	v_mul_f32_e32 v16, v16, v192
	v_mul_f32_e32 v48, v48, v193
	v_mul_f32_e32 v16, v16, v249
	v_mul_f32_e32 v48, v48, v250
	v_cvt_pk_bf16_f32 v80, v16, v48
	v_lshlrev_b32_e32 v251, 16, v81
	v_and_b32_e32 v252, s79, v81
	v_mul_f32_e32 v17, v17, v245
	v_mul_f32_e32 v49, v49, v245
	v_mul_f32_e32 v17, v17, v194
	v_mul_f32_e32 v49, v49, v195
	v_mul_f32_e32 v17, v17, v251
	v_mul_f32_e32 v49, v49, v252
	v_cvt_pk_bf16_f32 v81, v17, v49
	v_lshlrev_b32_e32 v249, 16, v82
	v_and_b32_e32 v250, s79, v82
	v_mul_f32_e32 v18, v18, v245
	v_mul_f32_e32 v50, v50, v245
	v_mul_f32_e32 v18, v18, v196
	v_mul_f32_e32 v50, v50, v197
	v_mul_f32_e32 v18, v18, v249
	v_mul_f32_e32 v50, v50, v250
	v_cvt_pk_bf16_f32 v82, v18, v50
	v_lshlrev_b32_e32 v251, 16, v83
	v_and_b32_e32 v252, s79, v83
	v_mul_f32_e32 v19, v19, v245
	v_mul_f32_e32 v51, v51, v245
	v_mul_f32_e32 v19, v19, v198
	v_mul_f32_e32 v51, v51, v199
	v_mul_f32_e32 v19, v19, v251
	v_mul_f32_e32 v51, v51, v252
	v_cvt_pk_bf16_f32 v83, v19, v51
	global_store_dwordx4 v215, v[80:83], s[28:29] nt
	v_lshlrev_b32_e32 v249, 16, v84
	v_and_b32_e32 v250, s79, v84
	v_mul_f32_e32 v20, v20, v246
	v_mul_f32_e32 v52, v52, v246
	v_mul_f32_e32 v20, v20, v192
	v_mul_f32_e32 v52, v52, v193
	v_mul_f32_e32 v20, v20, v249
	v_mul_f32_e32 v52, v52, v250
	v_cvt_pk_bf16_f32 v84, v20, v52
	v_lshlrev_b32_e32 v251, 16, v85
	v_and_b32_e32 v252, s79, v85
	v_mul_f32_e32 v21, v21, v246
	v_mul_f32_e32 v53, v53, v246
	v_mul_f32_e32 v21, v21, v194
	v_mul_f32_e32 v53, v53, v195
	v_mul_f32_e32 v21, v21, v251
	v_mul_f32_e32 v53, v53, v252
	v_cvt_pk_bf16_f32 v85, v21, v53
	v_lshlrev_b32_e32 v249, 16, v86
	v_and_b32_e32 v250, s79, v86
	v_mul_f32_e32 v22, v22, v246
	v_mul_f32_e32 v54, v54, v246
	v_mul_f32_e32 v22, v22, v196
	v_mul_f32_e32 v54, v54, v197
	v_mul_f32_e32 v22, v22, v249
	v_mul_f32_e32 v54, v54, v250
	v_cvt_pk_bf16_f32 v86, v22, v54
	v_lshlrev_b32_e32 v251, 16, v87
	v_and_b32_e32 v252, s79, v87
	v_mul_f32_e32 v23, v23, v246
	v_mul_f32_e32 v55, v55, v246
	v_mul_f32_e32 v23, v23, v198
	v_mul_f32_e32 v55, v55, v199
	v_mul_f32_e32 v23, v23, v251
	v_mul_f32_e32 v55, v55, v252
	v_cvt_pk_bf16_f32 v87, v23, v55
	global_store_dwordx4 v216, v[84:87], s[28:29] nt
	v_lshlrev_b32_e32 v249, 16, v88
	v_and_b32_e32 v250, s79, v88
	v_mul_f32_e32 v24, v24, v247
	v_mul_f32_e32 v56, v56, v247
	v_mul_f32_e32 v24, v24, v192
	v_mul_f32_e32 v56, v56, v193
	v_mul_f32_e32 v24, v24, v249
	v_mul_f32_e32 v56, v56, v250
	v_cvt_pk_bf16_f32 v88, v24, v56
	v_lshlrev_b32_e32 v251, 16, v89
	v_and_b32_e32 v252, s79, v89
	v_mul_f32_e32 v25, v25, v247
	v_mul_f32_e32 v57, v57, v247
	v_mul_f32_e32 v25, v25, v194
	v_mul_f32_e32 v57, v57, v195
	v_mul_f32_e32 v25, v25, v251
	v_mul_f32_e32 v57, v57, v252
	v_cvt_pk_bf16_f32 v89, v25, v57
	v_lshlrev_b32_e32 v249, 16, v90
	v_and_b32_e32 v250, s79, v90
	v_mul_f32_e32 v26, v26, v247
	v_mul_f32_e32 v58, v58, v247
	v_mul_f32_e32 v26, v26, v196
	v_mul_f32_e32 v58, v58, v197
	v_mul_f32_e32 v26, v26, v249
	v_mul_f32_e32 v58, v58, v250
	v_cvt_pk_bf16_f32 v90, v26, v58
	v_lshlrev_b32_e32 v251, 16, v91
	v_and_b32_e32 v252, s79, v91
	v_mul_f32_e32 v27, v27, v247
	v_mul_f32_e32 v59, v59, v247
	v_mul_f32_e32 v27, v27, v198
	v_mul_f32_e32 v59, v59, v199
	v_mul_f32_e32 v27, v27, v251
	v_mul_f32_e32 v59, v59, v252
	v_cvt_pk_bf16_f32 v91, v27, v59
	global_store_dwordx4 v217, v[88:91], s[28:29] nt
	v_lshlrev_b32_e32 v249, 16, v92
	v_and_b32_e32 v250, s79, v92
	v_mul_f32_e32 v28, v28, v248
	v_mul_f32_e32 v60, v60, v248
	v_mul_f32_e32 v28, v28, v192
	v_mul_f32_e32 v60, v60, v193
	v_mul_f32_e32 v28, v28, v249
	v_mul_f32_e32 v60, v60, v250
	v_cvt_pk_bf16_f32 v92, v28, v60
	v_lshlrev_b32_e32 v251, 16, v93
	v_and_b32_e32 v252, s79, v93
	v_mul_f32_e32 v29, v29, v248
	v_mul_f32_e32 v61, v61, v248
	v_mul_f32_e32 v29, v29, v194
	v_mul_f32_e32 v61, v61, v195
	v_mul_f32_e32 v29, v29, v251
	v_mul_f32_e32 v61, v61, v252
	v_cvt_pk_bf16_f32 v93, v29, v61
	v_lshlrev_b32_e32 v249, 16, v94
	v_and_b32_e32 v250, s79, v94
	v_mul_f32_e32 v30, v30, v248
	v_mul_f32_e32 v62, v62, v248
	v_mul_f32_e32 v30, v30, v196
	v_mul_f32_e32 v62, v62, v197
	v_mul_f32_e32 v30, v30, v249
	v_mul_f32_e32 v62, v62, v250
	v_cvt_pk_bf16_f32 v94, v30, v62
	v_lshlrev_b32_e32 v251, 16, v95
	v_and_b32_e32 v252, s79, v95
	v_mul_f32_e32 v31, v31, v248
	v_mul_f32_e32 v63, v63, v248
	v_mul_f32_e32 v31, v31, v198
	v_mul_f32_e32 v63, v63, v199
	v_mul_f32_e32 v31, v31, v251
	v_mul_f32_e32 v63, v63, v252
	v_cvt_pk_bf16_f32 v95, v31, v63
	global_store_dwordx4 v219, v[92:95], s[28:29] nt
	s_lshl_b32 s21, s75, 24
	s_lshl_b32 s32, s57, 20
	s_add_u32 s21, s21, s32
	s_lshl_b32 s32, s61, 1
	s_add_u32 s21, s21, s32
	s_add_u32 s21, s21, 0x15a00800
	s_add_u32 s28, s8, s21
	s_addc_u32 s29, s9, 0
	s_waitcnt vmcnt(8)
; __device__ __forceinline__ float bflo(unsigned w) { return __uint_as_float(w << 16); }
; __device__ __forceinline__ float bfhi(unsigned w) { return __uint_as_float(w & 0xffff0000u); }
; __global__ void __launch_bounds__(NWAVES * 64, 2) fwd_kernel(Args args) {
;     ...
;                         for (int it = 0; it < 8; ++it) { const size_t row = r0 + it * 4; const v4u p = pp[it], q = qq[it], z = zz[it];
;                             float d[8]; float ss = 0.f;
; #pragma unroll
;                             for (int e = 0; e < 4; ++e) { d[2 * e] = bflo(p[e]) - lam * bflo(q[e]); d[2 * e + 1] = bfhi(p[e]) - lam * bfhi(q[e]); ss += d[2 * e] * d[2 * e] + d[2 * e + 1] * d[2 * e + 1]; }
	v_lshlrev_b32_e32 v249, 16, v128
	v_and_b32_e32 v250, s79, v128
	v_lshlrev_b32_e32 v251, 16, v96
	v_and_b32_e32 v252, s79, v96
	v_fma_f32 v96, -s26, v249, v251
	v_fma_f32 v128, -s26, v250, v252
	v_lshlrev_b32_e32 v249, 16, v129
	v_and_b32_e32 v250, s79, v129
	v_lshlrev_b32_e32 v251, 16, v97
	v_and_b32_e32 v252, s79, v97
	v_mul_f32_e32 v241, v96, v96
	v_mul_f32_e32 v222, v128, v128
	v_fma_f32 v97, -s26, v249, v251
	v_fma_f32 v129, -s26, v250, v252
	v_lshlrev_b32_e32 v249, 16, v130
	v_and_b32_e32 v250, s79, v130
	v_lshlrev_b32_e32 v251, 16, v98
	v_and_b32_e32 v252, s79, v98
	v_fmac_f32_e32 v241, v97, v97
	v_fmac_f32_e32 v222, v129, v129
	v_fma_f32 v98, -s26, v249, v251
	v_fma_f32 v130, -s26, v250, v252
	v_lshlrev_b32_e32 v249, 16, v131
	v_and_b32_e32 v250, s79, v131
	v_lshlrev_b32_e32 v251, 16, v99
	v_and_b32_e32 v252, s79, v99
	v_fmac_f32_e32 v241, v98, v98
	v_fmac_f32_e32 v222, v130, v130
	v_fma_f32 v99, -s26, v249, v251
	v_fma_f32 v131, -s26, v250, v252
	s_nop 0
	v_fmac_f32_e32 v241, v99, v99
	v_fmac_f32_e32 v222, v131, v131
	v_lshlrev_b32_e32 v249, 16, v132
	v_and_b32_e32 v250, s79, v132
	v_lshlrev_b32_e32 v251, 16, v100
	v_and_b32_e32 v252, s79, v100
	v_fma_f32 v100, -s26, v249, v251
	v_fma_f32 v132, -s26, v250, v252
	v_lshlrev_b32_e32 v249, 16, v133
	v_and_b32_e32 v250, s79, v133
	v_lshlrev_b32_e32 v251, 16, v101
	v_and_b32_e32 v252, s79, v101
	v_mul_f32_e32 v242, v100, v100
	v_mul_f32_e32 v223, v132, v132
	v_fma_f32 v101, -s26, v249, v251
	v_fma_f32 v133, -s26, v250, v252
	v_lshlrev_b32_e32 v249, 16, v134
	v_and_b32_e32 v250, s79, v134
	v_lshlrev_b32_e32 v251, 16, v102
	v_and_b32_e32 v252, s79, v102
	v_fmac_f32_e32 v242, v101, v101
	v_fmac_f32_e32 v223, v133, v133
	v_fma_f32 v102, -s26, v249, v251
	v_fma_f32 v134, -s26, v250, v252
	v_lshlrev_b32_e32 v249, 16, v135
	v_and_b32_e32 v250, s79, v135
	v_lshlrev_b32_e32 v251, 16, v103
	v_and_b32_e32 v252, s79, v103
	v_fmac_f32_e32 v242, v102, v102
	v_fmac_f32_e32 v223, v134, v134
	v_fma_f32 v103, -s26, v249, v251
	v_fma_f32 v135, -s26, v250, v252
	s_nop 0
	v_fmac_f32_e32 v242, v103, v103
	v_fmac_f32_e32 v223, v135, v135
	v_lshlrev_b32_e32 v249, 16, v136
	v_and_b32_e32 v250, s79, v136
	v_lshlrev_b32_e32 v251, 16, v104
	v_and_b32_e32 v252, s79, v104
	v_fma_f32 v104, -s26, v249, v251
	v_fma_f32 v136, -s26, v250, v252
	v_lshlrev_b32_e32 v249, 16, v137
	v_and_b32_e32 v250, s79, v137
	v_lshlrev_b32_e32 v251, 16, v105
	v_and_b32_e32 v252, s79, v105
	v_mul_f32_e32 v243, v104, v104
	v_mul_f32_e32 v224, v136, v136
	v_fma_f32 v105, -s26, v249, v251
	v_fma_f32 v137, -s26, v250, v252
	v_lshlrev_b32_e32 v249, 16, v138
	v_and_b32_e32 v250, s79, v138
	v_lshlrev_b32_e32 v251, 16, v106
	v_and_b32_e32 v252, s79, v106
	v_fmac_f32_e32 v243, v105, v105
	v_fmac_f32_e32 v224, v137, v137
	v_fma_f32 v106, -s26, v249, v251
	v_fma_f32 v138, -s26, v250, v252
	v_lshlrev_b32_e32 v249, 16, v139
	v_and_b32_e32 v250, s79, v139
	v_lshlrev_b32_e32 v251, 16, v107
	v_and_b32_e32 v252, s79, v107
	v_fmac_f32_e32 v243, v106, v106
	v_fmac_f32_e32 v224, v138, v138
	v_fma_f32 v107, -s26, v249, v251
	v_fma_f32 v139, -s26, v250, v252
	s_nop 0
	v_fmac_f32_e32 v243, v107, v107
	v_fmac_f32_e32 v224, v139, v139
	v_lshlrev_b32_e32 v249, 16, v140
	v_and_b32_e32 v250, s79, v140
	v_lshlrev_b32_e32 v251, 16, v108
	v_and_b32_e32 v252, s79, v108
	v_fma_f32 v108, -s26, v249, v251
	v_fma_f32 v140, -s26, v250, v252
	v_lshlrev_b32_e32 v249, 16, v141
	v_and_b32_e32 v250, s79, v141
	v_lshlrev_b32_e32 v251, 16, v109
	v_and_b32_e32 v252, s79, v109
	v_mul_f32_e32 v244, v108, v108
	v_mul_f32_e32 v225, v140, v140
	v_fma_f32 v109, -s26, v249, v251
	v_fma_f32 v141, -s26, v250, v252
	v_lshlrev_b32_e32 v249, 16, v142
	v_and_b32_e32 v250, s79, v142
	v_lshlrev_b32_e32 v251, 16, v110
	v_and_b32_e32 v252, s79, v110
	v_fmac_f32_e32 v244, v109, v109
	v_fmac_f32_e32 v225, v141, v141
	v_fma_f32 v110, -s26, v249, v251
	v_fma_f32 v142, -s26, v250, v252
	v_lshlrev_b32_e32 v249, 16, v143
	v_and_b32_e32 v250, s79, v143
	v_lshlrev_b32_e32 v251, 16, v111
	v_and_b32_e32 v252, s79, v111
	v_fmac_f32_e32 v244, v110, v110
	v_fmac_f32_e32 v225, v142, v142
	v_fma_f32 v111, -s26, v249, v251
	v_fma_f32 v143, -s26, v250, v252
	s_nop 0
	v_fmac_f32_e32 v244, v111, v111
	v_fmac_f32_e32 v225, v143, v143
	v_lshlrev_b32_e32 v249, 16, v144
	v_and_b32_e32 v250, s79, v144
	v_lshlrev_b32_e32 v251, 16, v112
	v_and_b32_e32 v252, s79, v112
	v_fma_f32 v112, -s26, v249, v251
	v_fma_f32 v144, -s26, v250, v252
	v_lshlrev_b32_e32 v249, 16, v145
	v_and_b32_e32 v250, s79, v145
	v_lshlrev_b32_e32 v251, 16, v113
	v_and_b32_e32 v252, s79, v113
	v_mul_f32_e32 v245, v112, v112
	v_mul_f32_e32 v226, v144, v144
	v_fma_f32 v113, -s26, v249, v251
	v_fma_f32 v145, -s26, v250, v252
	v_lshlrev_b32_e32 v249, 16, v146
	v_and_b32_e32 v250, s79, v146
	v_lshlrev_b32_e32 v251, 16, v114
	v_and_b32_e32 v252, s79, v114
	v_fmac_f32_e32 v245, v113, v113
	v_fmac_f32_e32 v226, v145, v145
	v_fma_f32 v114, -s26, v249, v251
	v_fma_f32 v146, -s26, v250, v252
	v_lshlrev_b32_e32 v249, 16, v147
	v_and_b32_e32 v250, s79, v147
	v_lshlrev_b32_e32 v251, 16, v115
	v_and_b32_e32 v252, s79, v115
	v_fmac_f32_e32 v245, v114, v114
	v_fmac_f32_e32 v226, v146, v146
	v_fma_f32 v115, -s26, v249, v251
	v_fma_f32 v147, -s26, v250, v252
	s_nop 0
	v_fmac_f32_e32 v245, v115, v115
	v_fmac_f32_e32 v226, v147, v147
	v_lshlrev_b32_e32 v249, 16, v148
	v_and_b32_e32 v250, s79, v148
	v_lshlrev_b32_e32 v251, 16, v116
	v_and_b32_e32 v252, s79, v116
	v_fma_f32 v116, -s26, v249, v251
	v_fma_f32 v148, -s26, v250, v252
	v_lshlrev_b32_e32 v249, 16, v149
	v_and_b32_e32 v250, s79, v149
	v_lshlrev_b32_e32 v251, 16, v117
	v_and_b32_e32 v252, s79, v117
	v_mul_f32_e32 v246, v116, v116
; __device__ __forceinline__ float lane_xor(float v, int lane, int o) { return __int_as_float(__builtin_amdgcn_ds_bpermute((lane ^ o) << 2, __float_as_int(v))); }
; __device__ __forceinline__ float bflo(unsigned w) { return __uint_as_float(w << 16); }
; __device__ __forceinline__ float bfhi(unsigned w) { return __uint_as_float(w & 0xffff0000u); }
; __global__ void __launch_bounds__(NWAVES * 64, 2) fwd_kernel(Args args) {
;     ...
;                             for (int e = 0; e < 4; ++e) { d[2 * e] = bflo(p[e]) - lam * bflo(q[e]); d[2 * e + 1] = bfhi(p[e]) - lam * bfhi(q[e]); ss += d[2 * e] * d[2 * e] + d[2 * e + 1] * d[2 * e + 1]; }
;                             ss += lane_xor(ss, ln, 1); ss += lane_xor(ss, ln, 2); ss += lane_xor(ss, ln, 4); ss += lane_xor(ss, ln, 8);
;                             const float r = 1.0f / sqrtf(ss * (1.f / 128.f) + 1e-6f);
	v_mul_f32_e32 v227, v148, v148
	v_fma_f32 v117, -s26, v249, v251
	v_fma_f32 v149, -s26, v250, v252
	v_lshlrev_b32_e32 v249, 16, v150
	v_and_b32_e32 v250, s79, v150
	v_lshlrev_b32_e32 v251, 16, v118
	v_and_b32_e32 v252, s79, v118
	v_fmac_f32_e32 v246, v117, v117
	v_fmac_f32_e32 v227, v149, v149
	v_fma_f32 v118, -s26, v249, v251
	v_fma_f32 v150, -s26, v250, v252
	v_lshlrev_b32_e32 v249, 16, v151
	v_and_b32_e32 v250, s79, v151
	v_lshlrev_b32_e32 v251, 16, v119
	v_and_b32_e32 v252, s79, v119
	v_fmac_f32_e32 v246, v118, v118
	v_fmac_f32_e32 v227, v150, v150
	v_fma_f32 v119, -s26, v249, v251
	v_fma_f32 v151, -s26, v250, v252
	s_nop 0
	v_fmac_f32_e32 v246, v119, v119
	v_fmac_f32_e32 v227, v151, v151
	v_lshlrev_b32_e32 v249, 16, v152
	v_and_b32_e32 v250, s79, v152
	v_lshlrev_b32_e32 v251, 16, v120
	v_and_b32_e32 v252, s79, v120
	v_fma_f32 v120, -s26, v249, v251
	v_fma_f32 v152, -s26, v250, v252
	v_lshlrev_b32_e32 v249, 16, v153
	v_and_b32_e32 v250, s79, v153
	v_lshlrev_b32_e32 v251, 16, v121
	v_and_b32_e32 v252, s79, v121
	v_mul_f32_e32 v247, v120, v120
	v_mul_f32_e32 v228, v152, v152
	v_fma_f32 v121, -s26, v249, v251
	v_fma_f32 v153, -s26, v250, v252
	v_lshlrev_b32_e32 v249, 16, v154
	v_and_b32_e32 v250, s79, v154
	v_lshlrev_b32_e32 v251, 16, v122
	v_and_b32_e32 v252, s79, v122
	v_fmac_f32_e32 v247, v121, v121
	v_fmac_f32_e32 v228, v153, v153
	v_fma_f32 v122, -s26, v249, v251
	v_fma_f32 v154, -s26, v250, v252
	v_lshlrev_b32_e32 v249, 16, v155
	v_and_b32_e32 v250, s79, v155
	v_lshlrev_b32_e32 v251, 16, v123
	v_and_b32_e32 v252, s79, v123
	v_fmac_f32_e32 v247, v122, v122
	v_fmac_f32_e32 v228, v154, v154
	v_fma_f32 v123, -s26, v249, v251
	v_fma_f32 v155, -s26, v250, v252
	s_nop 0
	v_fmac_f32_e32 v247, v123, v123
	v_fmac_f32_e32 v228, v155, v155
	v_lshlrev_b32_e32 v249, 16, v156
	v_and_b32_e32 v250, s79, v156
	v_lshlrev_b32_e32 v251, 16, v124
	v_and_b32_e32 v252, s79, v124
	v_fma_f32 v124, -s26, v249, v251
	v_fma_f32 v156, -s26, v250, v252
	v_lshlrev_b32_e32 v249, 16, v157
	v_and_b32_e32 v250, s79, v157
	v_lshlrev_b32_e32 v251, 16, v125
	v_and_b32_e32 v252, s79, v125
	v_mul_f32_e32 v248, v124, v124
	v_mul_f32_e32 v229, v156, v156
	v_fma_f32 v125, -s26, v249, v251
	v_fma_f32 v157, -s26, v250, v252
	v_lshlrev_b32_e32 v249, 16, v158
	v_and_b32_e32 v250, s79, v158
	v_lshlrev_b32_e32 v251, 16, v126
	v_and_b32_e32 v252, s79, v126
	v_fmac_f32_e32 v248, v125, v125
	v_fmac_f32_e32 v229, v157, v157
	v_fma_f32 v126, -s26, v249, v251
	v_fma_f32 v158, -s26, v250, v252
	v_lshlrev_b32_e32 v249, 16, v159
	v_and_b32_e32 v250, s79, v159
	v_lshlrev_b32_e32 v251, 16, v127
	v_and_b32_e32 v252, s79, v127
	v_fmac_f32_e32 v248, v126, v126
	v_fmac_f32_e32 v229, v158, v158
	v_fma_f32 v127, -s26, v249, v251
	v_fma_f32 v159, -s26, v250, v252
	s_nop 0
	v_fmac_f32_e32 v248, v127, v127
	v_fmac_f32_e32 v229, v159, v159
	v_add_f32_e32 v241, v241, v222
	v_add_f32_e32 v242, v242, v223
	v_add_f32_e32 v243, v243, v224
	v_add_f32_e32 v244, v244, v225
	v_add_f32_e32 v245, v245, v226
	v_add_f32_e32 v246, v246, v227
	v_add_f32_e32 v247, v247, v228
	v_add_f32_e32 v248, v248, v229
	v_add_f32_dpp v241, v241, v241 quad_perm:[1,0,3,2] row_mask:0xf bank_mask:0xf
	v_add_f32_dpp v242, v242, v242 quad_perm:[1,0,3,2] row_mask:0xf bank_mask:0xf
	v_add_f32_dpp v243, v243, v243 quad_perm:[1,0,3,2] row_mask:0xf bank_mask:0xf
	v_add_f32_dpp v244, v244, v244 quad_perm:[1,0,3,2] row_mask:0xf bank_mask:0xf
	v_add_f32_dpp v245, v245, v245 quad_perm:[1,0,3,2] row_mask:0xf bank_mask:0xf
	v_add_f32_dpp v246, v246, v246 quad_perm:[1,0,3,2] row_mask:0xf bank_mask:0xf
	v_add_f32_dpp v247, v247, v247 quad_perm:[1,0,3,2] row_mask:0xf bank_mask:0xf
	v_add_f32_dpp v248, v248, v248 quad_perm:[1,0,3,2] row_mask:0xf bank_mask:0xf
	v_add_f32_dpp v241, v241, v241 quad_perm:[2,3,0,1] row_mask:0xf bank_mask:0xf
	v_add_f32_dpp v242, v242, v242 quad_perm:[2,3,0,1] row_mask:0xf bank_mask:0xf
	v_add_f32_dpp v243, v243, v243 quad_perm:[2,3,0,1] row_mask:0xf bank_mask:0xf
	v_add_f32_dpp v244, v244, v244 quad_perm:[2,3,0,1] row_mask:0xf bank_mask:0xf
	v_add_f32_dpp v245, v245, v245 quad_perm:[2,3,0,1] row_mask:0xf bank_mask:0xf
	v_add_f32_dpp v246, v246, v246 quad_perm:[2,3,0,1] row_mask:0xf bank_mask:0xf
	v_add_f32_dpp v247, v247, v247 quad_perm:[2,3,0,1] row_mask:0xf bank_mask:0xf
	v_add_f32_dpp v248, v248, v248 quad_perm:[2,3,0,1] row_mask:0xf bank_mask:0xf
	v_add_f32_dpp v241, v241, v241 row_ror:4 row_mask:0xf bank_mask:0xf
	v_add_f32_dpp v242, v242, v242 row_ror:4 row_mask:0xf bank_mask:0xf
	v_add_f32_dpp v243, v243, v243 row_ror:4 row_mask:0xf bank_mask:0xf
	v_add_f32_dpp v244, v244, v244 row_ror:4 row_mask:0xf bank_mask:0xf
	v_add_f32_dpp v245, v245, v245 row_ror:4 row_mask:0xf bank_mask:0xf
	v_add_f32_dpp v246, v246, v246 row_ror:4 row_mask:0xf bank_mask:0xf
	v_add_f32_dpp v247, v247, v247 row_ror:4 row_mask:0xf bank_mask:0xf
	v_add_f32_dpp v248, v248, v248 row_ror:4 row_mask:0xf bank_mask:0xf
	v_add_f32_dpp v241, v241, v241 row_ror:8 row_mask:0xf bank_mask:0xf
	v_add_f32_dpp v242, v242, v242 row_ror:8 row_mask:0xf bank_mask:0xf
	v_add_f32_dpp v243, v243, v243 row_ror:8 row_mask:0xf bank_mask:0xf
	v_add_f32_dpp v244, v244, v244 row_ror:8 row_mask:0xf bank_mask:0xf
	v_add_f32_dpp v245, v245, v245 row_ror:8 row_mask:0xf bank_mask:0xf
	v_add_f32_dpp v246, v246, v246 row_ror:8 row_mask:0xf bank_mask:0xf
	v_add_f32_dpp v247, v247, v247 row_ror:8 row_mask:0xf bank_mask:0xf
	v_add_f32_dpp v248, v248, v248 row_ror:8 row_mask:0xf bank_mask:0xf
	v_fmamk_f32 v241, v241, 0x3c000000, v231
	v_fmamk_f32 v242, v242, 0x3c000000, v231
	v_fmamk_f32 v243, v243, 0x3c000000, v231
	v_fmamk_f32 v244, v244, 0x3c000000, v231
; #define GASP __attribute__((address_space(1)))
; __device__ __forceinline__ float lane_xor(float v, int lane, int o) { return __int_as_float(__builtin_amdgcn_ds_bpermute((lane ^ o) << 2, __float_as_int(v))); }
; __device__ __forceinline__ unsigned pk2(float lo, float hi) { return f2bf(lo) | (f2bf(hi) << 16); }
; __device__ __forceinline__ float bflo(unsigned w) { return __uint_as_float(w << 16); }
; __device__ __forceinline__ float bfhi(unsigned w) { return __uint_as_float(w & 0xffff0000u); }
; __global__ void __launch_bounds__(NWAVES * 64, 2) fwd_kernel(Args args) {
;     ...
;                             ss += lane_xor(ss, ln, 1); ss += lane_xor(ss, ln, 2); ss += lane_xor(ss, ln, 4); ss += lane_xor(ss, ln, 8);
;                             const float r = 1.0f / sqrtf(ss * (1.f / 128.f) + 1e-6f);
;                             v4u o;
;                             o[0] = pk2(d[0] * r * sg0[0] * bflo(z[0]), d[1] * r * sg0[1] * bfhi(z[0])); o[1] = pk2(d[2] * r * sg0[2] * bflo(z[1]), d[3] * r * sg0[3] * bfhi(z[1]));
;                             o[2] = pk2(d[4] * r * sg1[0] * bflo(z[2]), d[5] * r * sg1[1] * bfhi(z[2])); o[3] = pk2(d[6] * r * sg1[2] * bflo(z[3]), d[7] * r * sg1[3] * bfhi(z[3]));
;                             *(GASP v4u*)(YCAT + row * 2048 + 1024 + h * 128 + c8) = o; }
	v_fmamk_f32 v245, v245, 0x3c000000, v231
	v_fmamk_f32 v246, v246, 0x3c000000, v231
	v_fmamk_f32 v247, v247, 0x3c000000, v231
	v_fmamk_f32 v248, v248, 0x3c000000, v231
	v_rsq_f32_e32 v241, v241
	v_rsq_f32_e32 v242, v242
	v_rsq_f32_e32 v243, v243
	v_rsq_f32_e32 v244, v244
	v_rsq_f32_e32 v245, v245
	v_rsq_f32_e32 v246, v246
	v_rsq_f32_e32 v247, v247
	v_rsq_f32_e32 v248, v248
	v_lshlrev_b32_e32 v249, 16, v160
	v_and_b32_e32 v250, s79, v160
	v_mul_f32_e32 v96, v96, v241
	v_mul_f32_e32 v128, v128, v241
	v_mul_f32_e32 v96, v96, v192
	v_mul_f32_e32 v128, v128, v193
	v_mul_f32_e32 v96, v96, v249
	v_mul_f32_e32 v128, v128, v250
	v_cvt_pk_bf16_f32 v160, v96, v128
	v_lshlrev_b32_e32 v251, 16, v161
	v_and_b32_e32 v252, s79, v161
	v_mul_f32_e32 v97, v97, v241
	v_mul_f32_e32 v129, v129, v241
	v_mul_f32_e32 v97, v97, v194
	v_mul_f32_e32 v129, v129, v195
	v_mul_f32_e32 v97, v97, v251
	v_mul_f32_e32 v129, v129, v252
	v_cvt_pk_bf16_f32 v161, v97, v129
	v_lshlrev_b32_e32 v249, 16, v162
	v_and_b32_e32 v250, s79, v162
	v_mul_f32_e32 v98, v98, v241
	v_mul_f32_e32 v130, v130, v241
	v_mul_f32_e32 v98, v98, v196
	v_mul_f32_e32 v130, v130, v197
	v_mul_f32_e32 v98, v98, v249
	v_mul_f32_e32 v130, v130, v250
	v_cvt_pk_bf16_f32 v162, v98, v130
	v_lshlrev_b32_e32 v251, 16, v163
	v_and_b32_e32 v252, s79, v163
	v_mul_f32_e32 v99, v99, v241
	v_mul_f32_e32 v131, v131, v241
	v_mul_f32_e32 v99, v99, v198
	v_mul_f32_e32 v131, v131, v199
	v_mul_f32_e32 v99, v99, v251
	v_mul_f32_e32 v131, v131, v252
	v_cvt_pk_bf16_f32 v163, v99, v131
	global_store_dwordx4 v209, v[160:163], s[28:29] nt
	v_lshlrev_b32_e32 v249, 16, v164
	v_and_b32_e32 v250, s79, v164
	v_mul_f32_e32 v100, v100, v242
	v_mul_f32_e32 v132, v132, v242
	v_mul_f32_e32 v100, v100, v192
	v_mul_f32_e32 v132, v132, v193
	v_mul_f32_e32 v100, v100, v249
	v_mul_f32_e32 v132, v132, v250
	v_cvt_pk_bf16_f32 v164, v100, v132
	v_lshlrev_b32_e32 v251, 16, v165
	v_and_b32_e32 v252, s79, v165
	v_mul_f32_e32 v101, v101, v242
	v_mul_f32_e32 v133, v133, v242
	v_mul_f32_e32 v101, v101, v194
	v_mul_f32_e32 v133, v133, v195
	v_mul_f32_e32 v101, v101, v251
	v_mul_f32_e32 v133, v133, v252
	v_cvt_pk_bf16_f32 v165, v101, v133
	v_lshlrev_b32_e32 v249, 16, v166
	v_and_b32_e32 v250, s79, v166
	v_mul_f32_e32 v102, v102, v242
	v_mul_f32_e32 v134, v134, v242
	v_mul_f32_e32 v102, v102, v196
	v_mul_f32_e32 v134, v134, v197
	v_mul_f32_e32 v102, v102, v249
	v_mul_f32_e32 v134, v134, v250
	v_cvt_pk_bf16_f32 v166, v102, v134
	v_lshlrev_b32_e32 v251, 16, v167
	v_and_b32_e32 v252, s79, v167
	v_mul_f32_e32 v103, v103, v242
	v_mul_f32_e32 v135, v135, v242
	v_mul_f32_e32 v103, v103, v198
	v_mul_f32_e32 v135, v135, v199
	v_mul_f32_e32 v103, v103, v251
	v_mul_f32_e32 v135, v135, v252
	v_cvt_pk_bf16_f32 v167, v103, v135
	global_store_dwordx4 v210, v[164:167], s[28:29] nt
	v_lshlrev_b32_e32 v249, 16, v168
	v_and_b32_e32 v250, s79, v168
	v_mul_f32_e32 v104, v104, v243
	v_mul_f32_e32 v136, v136, v243
	v_mul_f32_e32 v104, v104, v192
	v_mul_f32_e32 v136, v136, v193
	v_mul_f32_e32 v104, v104, v249
	v_mul_f32_e32 v136, v136, v250
	v_cvt_pk_bf16_f32 v168, v104, v136
	v_lshlrev_b32_e32 v251, 16, v169
	v_and_b32_e32 v252, s79, v169
	v_mul_f32_e32 v105, v105, v243
	v_mul_f32_e32 v137, v137, v243
	v_mul_f32_e32 v105, v105, v194
	v_mul_f32_e32 v137, v137, v195
	v_mul_f32_e32 v105, v105, v251
	v_mul_f32_e32 v137, v137, v252
	v_cvt_pk_bf16_f32 v169, v105, v137
	v_lshlrev_b32_e32 v249, 16, v170
	v_and_b32_e32 v250, s79, v170
	v_mul_f32_e32 v106, v106, v243
	v_mul_f32_e32 v138, v138, v243
	v_mul_f32_e32 v106, v106, v196
	v_mul_f32_e32 v138, v138, v197
	v_mul_f32_e32 v106, v106, v249
	v_mul_f32_e32 v138, v138, v250
	v_cvt_pk_bf16_f32 v170, v106, v138
	v_lshlrev_b32_e32 v251, 16, v171
	v_and_b32_e32 v252, s79, v171
	v_mul_f32_e32 v107, v107, v243
	v_mul_f32_e32 v139, v139, v243
	v_mul_f32_e32 v107, v107, v198
	v_mul_f32_e32 v139, v139, v199
	v_mul_f32_e32 v107, v107, v251
	v_mul_f32_e32 v139, v139, v252
	v_cvt_pk_bf16_f32 v171, v107, v139
	global_store_dwordx4 v211, v[168:171], s[28:29] nt
	v_lshlrev_b32_e32 v249, 16, v172
	v_and_b32_e32 v250, s79, v172
	v_mul_f32_e32 v108, v108, v244
	v_mul_f32_e32 v140, v140, v244
	v_mul_f32_e32 v108, v108, v192
	v_mul_f32_e32 v140, v140, v193
	v_mul_f32_e32 v108, v108, v249
	v_mul_f32_e32 v140, v140, v250
	v_cvt_pk_bf16_f32 v172, v108, v140
	v_lshlrev_b32_e32 v251, 16, v173
	v_and_b32_e32 v252, s79, v173
	v_mul_f32_e32 v109, v109, v244
	v_mul_f32_e32 v141, v141, v244
	v_mul_f32_e32 v109, v109, v194
	v_mul_f32_e32 v141, v141, v195
	v_mul_f32_e32 v109, v109, v251
	v_mul_f32_e32 v141, v141, v252
	v_cvt_pk_bf16_f32 v173, v109, v141
	v_lshlrev_b32_e32 v249, 16, v174
	v_and_b32_e32 v250, s79, v174
	v_mul_f32_e32 v110, v110, v244
	v_mul_f32_e32 v142, v142, v244
	v_mul_f32_e32 v110, v110, v196
	v_mul_f32_e32 v142, v142, v197
	v_mul_f32_e32 v110, v110, v249
	v_mul_f32_e32 v142, v142, v250
	v_cvt_pk_bf16_f32 v174, v110, v142
	v_lshlrev_b32_e32 v251, 16, v175
	v_and_b32_e32 v252, s79, v175
	v_mul_f32_e32 v111, v111, v244
	v_mul_f32_e32 v143, v143, v244
	v_mul_f32_e32 v111, v111, v198
	v_mul_f32_e32 v143, v143, v199
; #define GASP __attribute__((address_space(1)))
; __device__ __forceinline__ unsigned pk2(float lo, float hi) { return f2bf(lo) | (f2bf(hi) << 16); }
; __device__ __forceinline__ float bflo(unsigned w) { return __uint_as_float(w << 16); }
; __device__ __forceinline__ float bfhi(unsigned w) { return __uint_as_float(w & 0xffff0000u); }
; __global__ void __launch_bounds__(NWAVES * 64, 2) fwd_kernel(Args args) {
;     ...
;                             o[0] = pk2(d[0] * r * sg0[0] * bflo(z[0]), d[1] * r * sg0[1] * bfhi(z[0])); o[1] = pk2(d[2] * r * sg0[2] * bflo(z[1]), d[3] * r * sg0[3] * bfhi(z[1]));
;                             o[2] = pk2(d[4] * r * sg1[0] * bflo(z[2]), d[5] * r * sg1[1] * bfhi(z[2])); o[3] = pk2(d[6] * r * sg1[2] * bflo(z[3]), d[7] * r * sg1[3] * bfhi(z[3]));
;                             *(GASP v4u*)(YCAT + row * 2048 + 1024 + h * 128 + c8) = o; }
	v_mul_f32_e32 v111, v111, v251
	v_mul_f32_e32 v143, v143, v252
	v_cvt_pk_bf16_f32 v175, v111, v143
	global_store_dwordx4 v214, v[172:175], s[28:29] nt
	v_lshlrev_b32_e32 v249, 16, v176
	v_and_b32_e32 v250, s79, v176
	v_mul_f32_e32 v112, v112, v245
	v_mul_f32_e32 v144, v144, v245
	v_mul_f32_e32 v112, v112, v192
	v_mul_f32_e32 v144, v144, v193
	v_mul_f32_e32 v112, v112, v249
	v_mul_f32_e32 v144, v144, v250
	v_cvt_pk_bf16_f32 v176, v112, v144
	v_lshlrev_b32_e32 v251, 16, v177
	v_and_b32_e32 v252, s79, v177
	v_mul_f32_e32 v113, v113, v245
	v_mul_f32_e32 v145, v145, v245
	v_mul_f32_e32 v113, v113, v194
	v_mul_f32_e32 v145, v145, v195
	v_mul_f32_e32 v113, v113, v251
	v_mul_f32_e32 v145, v145, v252
	v_cvt_pk_bf16_f32 v177, v113, v145
	v_lshlrev_b32_e32 v249, 16, v178
	v_and_b32_e32 v250, s79, v178
	v_mul_f32_e32 v114, v114, v245
	v_mul_f32_e32 v146, v146, v245
	v_mul_f32_e32 v114, v114, v196
	v_mul_f32_e32 v146, v146, v197
	v_mul_f32_e32 v114, v114, v249
	v_mul_f32_e32 v146, v146, v250
	v_cvt_pk_bf16_f32 v178, v114, v146
	v_lshlrev_b32_e32 v251, 16, v179
	v_and_b32_e32 v252, s79, v179
	v_mul_f32_e32 v115, v115, v245
	v_mul_f32_e32 v147, v147, v245
	v_mul_f32_e32 v115, v115, v198
	v_mul_f32_e32 v147, v147, v199
	v_mul_f32_e32 v115, v115, v251
	v_mul_f32_e32 v147, v147, v252
	v_cvt_pk_bf16_f32 v179, v115, v147
	global_store_dwordx4 v215, v[176:179], s[28:29] nt
	v_lshlrev_b32_e32 v249, 16, v180
	v_and_b32_e32 v250, s79, v180
	v_mul_f32_e32 v116, v116, v246
	v_mul_f32_e32 v148, v148, v246
	v_mul_f32_e32 v116, v116, v192
	v_mul_f32_e32 v148, v148, v193
	v_mul_f32_e32 v116, v116, v249
	v_mul_f32_e32 v148, v148, v250
	v_cvt_pk_bf16_f32 v180, v116, v148
	v_lshlrev_b32_e32 v251, 16, v181
	v_and_b32_e32 v252, s79, v181
	v_mul_f32_e32 v117, v117, v246
	v_mul_f32_e32 v149, v149, v246
	v_mul_f32_e32 v117, v117, v194
	v_mul_f32_e32 v149, v149, v195
	v_mul_f32_e32 v117, v117, v251
	v_mul_f32_e32 v149, v149, v252
	v_cvt_pk_bf16_f32 v181, v117, v149
	v_lshlrev_b32_e32 v249, 16, v182
	v_and_b32_e32 v250, s79, v182
	v_mul_f32_e32 v118, v118, v246
	v_mul_f32_e32 v150, v150, v246
	v_mul_f32_e32 v118, v118, v196
	v_mul_f32_e32 v150, v150, v197
	v_mul_f32_e32 v118, v118, v249
	v_mul_f32_e32 v150, v150, v250
	v_cvt_pk_bf16_f32 v182, v118, v150
	v_lshlrev_b32_e32 v251, 16, v183
	v_and_b32_e32 v252, s79, v183
	v_mul_f32_e32 v119, v119, v246
	v_mul_f32_e32 v151, v151, v246
	v_mul_f32_e32 v119, v119, v198
	v_mul_f32_e32 v151, v151, v199
	v_mul_f32_e32 v119, v119, v251
	v_mul_f32_e32 v151, v151, v252
	v_cvt_pk_bf16_f32 v183, v119, v151
	global_store_dwordx4 v216, v[180:183], s[28:29] nt
	v_lshlrev_b32_e32 v249, 16, v184
	v_and_b32_e32 v250, s79, v184
	v_mul_f32_e32 v120, v120, v247
	v_mul_f32_e32 v152, v152, v247
	v_mul_f32_e32 v120, v120, v192
	v_mul_f32_e32 v152, v152, v193
	v_mul_f32_e32 v120, v120, v249
	v_mul_f32_e32 v152, v152, v250
	v_cvt_pk_bf16_f32 v184, v120, v152
	v_lshlrev_b32_e32 v251, 16, v185
	v_and_b32_e32 v252, s79, v185
	v_mul_f32_e32 v121, v121, v247
	v_mul_f32_e32 v153, v153, v247
	v_mul_f32_e32 v121, v121, v194
	v_mul_f32_e32 v153, v153, v195
	v_mul_f32_e32 v121, v121, v251
	v_mul_f32_e32 v153, v153, v252
	v_cvt_pk_bf16_f32 v185, v121, v153
	v_lshlrev_b32_e32 v249, 16, v186
	v_and_b32_e32 v250, s79, v186
	v_mul_f32_e32 v122, v122, v247
	v_mul_f32_e32 v154, v154, v247
	v_mul_f32_e32 v122, v122, v196
	v_mul_f32_e32 v154, v154, v197
	v_mul_f32_e32 v122, v122, v249
	v_mul_f32_e32 v154, v154, v250
	v_cvt_pk_bf16_f32 v186, v122, v154
	v_lshlrev_b32_e32 v251, 16, v187
	v_and_b32_e32 v252, s79, v187
	v_mul_f32_e32 v123, v123, v247
	v_mul_f32_e32 v155, v155, v247
	v_mul_f32_e32 v123, v123, v198
	v_mul_f32_e32 v155, v155, v199
	v_mul_f32_e32 v123, v123, v251
	v_mul_f32_e32 v155, v155, v252
	v_cvt_pk_bf16_f32 v187, v123, v155
	global_store_dwordx4 v217, v[184:187], s[28:29] nt
	v_lshlrev_b32_e32 v249, 16, v188
	v_and_b32_e32 v250, s79, v188
	v_mul_f32_e32 v124, v124, v248
	v_mul_f32_e32 v156, v156, v248
	v_mul_f32_e32 v124, v124, v192
	v_mul_f32_e32 v156, v156, v193
	v_mul_f32_e32 v124, v124, v249
	v_mul_f32_e32 v156, v156, v250
	v_cvt_pk_bf16_f32 v188, v124, v156
	v_lshlrev_b32_e32 v251, 16, v189
	v_and_b32_e32 v252, s79, v189
	v_mul_f32_e32 v125, v125, v248
	v_mul_f32_e32 v157, v157, v248
	v_mul_f32_e32 v125, v125, v194
	v_mul_f32_e32 v157, v157, v195
	v_mul_f32_e32 v125, v125, v251
	v_mul_f32_e32 v157, v157, v252
	v_cvt_pk_bf16_f32 v189, v125, v157
	v_lshlrev_b32_e32 v249, 16, v190
	v_and_b32_e32 v250, s79, v190
	v_mul_f32_e32 v126, v126, v248
	v_mul_f32_e32 v158, v158, v248
	v_mul_f32_e32 v126, v126, v196
	v_mul_f32_e32 v158, v158, v197
	v_mul_f32_e32 v126, v126, v249
	v_mul_f32_e32 v158, v158, v250
	v_cvt_pk_bf16_f32 v190, v126, v158
	v_lshlrev_b32_e32 v251, 16, v191
	v_and_b32_e32 v252, s79, v191
	v_mul_f32_e32 v127, v127, v248
	v_mul_f32_e32 v159, v159, v248
	v_mul_f32_e32 v127, v127, v198
	v_mul_f32_e32 v159, v159, v199
	v_mul_f32_e32 v127, v127, v251
	v_mul_f32_e32 v159, v159, v252
	v_cvt_pk_bf16_f32 v191, v127, v159
	global_store_dwordx4 v219, v[188:191], s[28:29] nt
	s_branch .LBB0_398
